# GEMM mainloops: dropped the 16 no-op s_setprio 0 / s_setprio 1 pairs that sat between the two MFMA groups of each phase
# speedup vs baseline: 1.0075x; 1.0025x over previous
; #define PG8_STAGE(bufoff, gbase, voff) do { _Pragma("unroll") for (int _i = 0; _i < 2; ++_i) \
;         __builtin_amdgcn_global_load_lds((const unsigned*)((const char*)(gbase) + (voff)[_i]), (LAS unsigned*)(lds + (bufoff) + ldsw + _i * 8192), 16, 0, 0); } while (0)
; #define PG8_LDA(dst, b, h) do { _Pragma("unroll") for (int m = 0; m < 4; ++m) _Pragma("unroll") for (int k = 0; k < 2; ++k) dst[m][k] = *(const LAS bf16x8*)(lds + PG8_SA(b, h) + aoff + m * 2048 + k * 1024); } while (0)
; #define PG8_LDB(dst, b, h) do { _Pragma("unroll") for (int n = 0; n < 2; ++n) _Pragma("unroll") for (int k = 0; k < 2; ++k) dst[n][k] = *(const LAS bf16x8*)(lds + PG8_SB(b, h) + boff + n * 2048 + k * 1024); } while (0)
; #define PG8_MMA(ai, bj, At, Bt) do { __builtin_amdgcn_s_setprio(1); _Pragma("unroll") for (int m = 0; m < 4; ++m) _Pragma("unroll") for (int n = 0; n < 2; ++n) _Pragma("unroll") for (int k = 0; k < 2; ++k) \
;         acc[ai][bj][m][n] = __builtin_amdgcn_mfma_f32_16x16x32_bf16(Bt[n][k], At[m][k], acc[ai][bj][m][n], 0, 0, 0); __builtin_amdgcn_s_setprio(0); } while (0)
; #define PG8_WAIT_V(n) asm volatile("s_waitcnt vmcnt(" #n ")" ::: "memory")
; #define PG8_WAIT_L(n) asm volatile("s_waitcnt lgkmcnt(" #n ")" ::: "memory")
; #define PG8_BAR __builtin_amdgcn_s_barrier()
; #define PG8_SCHED __builtin_amdgcn_sched_barrier(0)
; template <class Epi>
; __device__ __forceinline__ void gemm_phase(LAS unsigned char* lds, const Gemm g, const StaticOrder& S, const Epi& E, const int tid) {
;     ...
;         for (int t = 0; t < nt; t += 2) {
;             const bool last = (t == nt - 2);
;             const char* a1 = cA + (size_t)(t + 1) * kstep + ((t + 1) >= 8 ? xtra : 0);
;             const char* a2 = last ? nA : cA + (size_t)(t + 2) * kstep + ((t + 2) >= 8 ? xtra : 0); const char* b2 = last ? nB : cB + (size_t)(t + 2) * kstep;
;             const char* a3 = a2 + kstep; const char* b3 = b2 + kstep;
;             PG8_LDB(B0, 0, 0); PG8_LDB(B1, 0, 1); PG8_SCHED; PG8_LDA(At, 0, 0); PG8_STAGE(PG8_SA(1, 1), a1 + hstepA, voffA);
;             PG8_WAIT_V(8); PG8_WAIT_L(0); PG8_BAR; PG8_MMA(0, 0, At, B0); PG8_MMA(0, 1, At, B1); PG8_BAR; PG8_SCHED;
;             PG8_LDA(At, 0, 1); PG8_STAGE(PG8_SB(0, 0), b2, voffB); PG8_STAGE(PG8_SB(0, 1), b2 + hstepB, voffB); PG8_STAGE(PG8_SA(0, 0), a2, voffA);
.LBB0_160:
	s_add_u32 s42, s94, 0x100
	s_addc_u32 s43, s95, 0
	s_add_i32 s8, 0, 0x10000
	v_add_u32_e32 v142, s8, v245
	v_add_u32_e32 v158, s15, v245
	ds_read_b128 v[122:125], v142
	ds_read_b128 v[126:129], v142 offset:1024
	ds_read_b128 v[138:141], v142 offset:2048
	ds_read_b128 v[142:145], v142 offset:3072
	ds_read_b128 v[146:149], v158
	ds_read_b128 v[150:153], v158 offset:1024
	ds_read_b128 v[154:157], v158 offset:2048
	ds_read_b128 v[158:161], v158 offset:3072
	s_cmp_eq_u32 s89, 12
	s_cselect_b32 vcc_hi, s91, s43
	s_cselect_b32 vcc_lo, s90, s42
	s_cselect_b32 s93, s36, s46
	s_cselect_b32 s92, s37, s45
	v_lshl_add_u64 v[210:211], s[94:95], 0, v[206:207]
	s_add_i32 m0, s19, 0xc000
	ds_read_b128 v[162:165], v246
	ds_read_b128 v[166:169], v246 offset:1024
	ds_read_b128 v[170:173], v246 offset:2048
	ds_read_b128 v[174:177], v246 offset:3072
	ds_read_b128 v[178:181], v246 offset:4096
	ds_read_b128 v[182:185], v246 offset:5120
	ds_read_b128 v[186:189], v246 offset:6144
	ds_read_b128 v[190:193], v246 offset:7168
	global_load_lds_dwordx4 v[210:211], off
	v_lshl_add_u64 v[210:211], s[94:95], 0, v[208:209]
	s_add_i32 m0, s19, 0xe000
	s_nop 0
	global_load_lds_dwordx4 v[210:211], off
	s_waitcnt vmcnt(8)
	s_waitcnt lgkmcnt(0)
	s_barrier
	s_setprio 1
	s_waitcnt lgkmcnt(0)
	v_mfma_f32_16x16x32_bf16 v[134:137], v[122:125], v[162:165], v[134:137]
	v_mfma_f32_16x16x32_bf16 v[130:133], v[138:141], v[162:165], v[130:133]
	v_mfma_f32_16x16x32_bf16 v[108:111], v[122:125], v[170:173], v[108:111]
	v_mfma_f32_16x16x32_bf16 v[104:107], v[138:141], v[170:173], v[104:107]
	v_mfma_f32_16x16x32_bf16 v[92:95], v[122:125], v[178:181], v[92:95]
	v_mfma_f32_16x16x32_bf16 v[88:91], v[138:141], v[178:181], v[88:91]
	v_mfma_f32_16x16x32_bf16 v[76:79], v[122:125], v[186:189], v[76:79]
	v_mfma_f32_16x16x32_bf16 v[72:75], v[138:141], v[186:189], v[72:75]
	v_mfma_f32_16x16x32_bf16 v[134:137], v[126:129], v[166:169], v[134:137]
	v_mfma_f32_16x16x32_bf16 v[130:133], v[142:145], v[166:169], v[130:133]
	v_mfma_f32_16x16x32_bf16 v[108:111], v[126:129], v[174:177], v[108:111]
	v_mfma_f32_16x16x32_bf16 v[104:107], v[142:145], v[174:177], v[104:107]
	v_mfma_f32_16x16x32_bf16 v[92:95], v[126:129], v[182:185], v[92:95]
	v_mfma_f32_16x16x32_bf16 v[88:91], v[142:145], v[182:185], v[88:91]
	v_mfma_f32_16x16x32_bf16 v[76:79], v[126:129], v[190:193], v[76:79]
	v_mfma_f32_16x16x32_bf16 v[72:75], v[142:145], v[190:193], v[72:75]
	v_mfma_f32_16x16x32_bf16 v[118:121], v[146:149], v[162:165], v[118:121]
	v_mfma_f32_16x16x32_bf16 v[114:117], v[154:157], v[162:165], v[114:117]
	v_mfma_f32_16x16x32_bf16 v[100:103], v[146:149], v[170:173], v[100:103]
	v_mfma_f32_16x16x32_bf16 v[96:99], v[154:157], v[170:173], v[96:99]
	v_mfma_f32_16x16x32_bf16 v[84:87], v[146:149], v[178:181], v[84:87]
	v_mfma_f32_16x16x32_bf16 v[80:83], v[154:157], v[178:181], v[80:83]
	v_mfma_f32_16x16x32_bf16 v[68:71], v[146:149], v[186:189], v[68:71]
	v_mfma_f32_16x16x32_bf16 v[64:67], v[154:157], v[186:189], v[64:67]
	v_mfma_f32_16x16x32_bf16 v[118:121], v[150:153], v[166:169], v[118:121]
	v_mfma_f32_16x16x32_bf16 v[114:117], v[158:161], v[166:169], v[114:117]
	v_mfma_f32_16x16x32_bf16 v[100:103], v[150:153], v[174:177], v[100:103]
	v_mfma_f32_16x16x32_bf16 v[96:99], v[158:161], v[174:177], v[96:99]
	v_mfma_f32_16x16x32_bf16 v[84:87], v[150:153], v[182:185], v[84:87]
	v_mfma_f32_16x16x32_bf16 v[80:83], v[158:161], v[182:185], v[80:83]
	v_mfma_f32_16x16x32_bf16 v[68:71], v[150:153], v[190:193], v[68:71]
	v_mfma_f32_16x16x32_bf16 v[64:67], v[158:161], v[190:193], v[64:67]
	s_setprio 0
	s_barrier
	s_add_i32 s8, s8, s11
	v_lshl_add_u64 v[210:211], s[92:93], 0, v[112:113]
	s_mov_b32 m0, s8
	ds_read_b128 v[162:165], v246 offset:16384
	ds_read_b128 v[166:169], v246 offset:17408
	ds_read_b128 v[170:173], v246 offset:18432
	ds_read_b128 v[174:177], v246 offset:19456
	ds_read_b128 v[178:181], v246 offset:20480
	ds_read_b128 v[182:185], v246 offset:21504
	ds_read_b128 v[186:189], v246 offset:22528
	ds_read_b128 v[190:193], v246 offset:23552
	global_load_lds_dwordx4 v112, s[92:93]
	s_add_i32 m0, s8, 0x2000
	s_add_u32 s8, s92, 0x40000
	v_lshl_add_u64 v[212:213], s[92:93], 0, v[200:201]
	s_addc_u32 s9, s93, 0
	s_add_i32 s13, s15, s11
	global_load_lds_dwordx4 v200, s[92:93]
	s_nop 0
	s_mov_b32 m0, s13
	v_lshl_add_u64 v[228:229], vcc, 0, v[204:205]
	global_load_lds_dwordx4 v112, s[8:9]
	s_nop 0
	s_add_i32 m0, s13, 0x2000
	s_nop 0
	global_load_lds_dwordx4 v200, s[8:9]
	v_lshl_add_u64 v[214:215], vcc, 0, v[202:203]
	s_mov_b32 m0, s19
	s_nop 0
	global_load_lds_dwordx4 v202, vcc
	s_mov_b32 m0, s28
	s_nop 0
	global_load_lds_dwordx4 v204, vcc
	s_waitcnt vmcnt(8)
	s_waitcnt lgkmcnt(0)
	s_barrier
; #define PG8_STAGE(bufoff, gbase, voff) do { _Pragma("unroll") for (int _i = 0; _i < 2; ++_i) \
;         __builtin_amdgcn_global_load_lds((const unsigned*)((const char*)(gbase) + (voff)[_i]), (LAS unsigned*)(lds + (bufoff) + ldsw + _i * 8192), 16, 0, 0); } while (0)
; #define PG8_LDA(dst, b, h) do { _Pragma("unroll") for (int m = 0; m < 4; ++m) _Pragma("unroll") for (int k = 0; k < 2; ++k) dst[m][k] = *(const LAS bf16x8*)(lds + PG8_SA(b, h) + aoff + m * 2048 + k * 1024); } while (0)
; #define PG8_LDB(dst, b, h) do { _Pragma("unroll") for (int n = 0; n < 2; ++n) _Pragma("unroll") for (int k = 0; k < 2; ++k) dst[n][k] = *(const LAS bf16x8*)(lds + PG8_SB(b, h) + boff + n * 2048 + k * 1024); } while (0)
; #define PG8_MMA(ai, bj, At, Bt) do { __builtin_amdgcn_s_setprio(1); _Pragma("unroll") for (int m = 0; m < 4; ++m) _Pragma("unroll") for (int n = 0; n < 2; ++n) _Pragma("unroll") for (int k = 0; k < 2; ++k) \
;         acc[ai][bj][m][n] = __builtin_amdgcn_mfma_f32_16x16x32_bf16(Bt[n][k], At[m][k], acc[ai][bj][m][n], 0, 0, 0); __builtin_amdgcn_s_setprio(0); } while (0)
; #define PG8_WAIT_V(n) asm volatile("s_waitcnt vmcnt(" #n ")" ::: "memory")
; #define PG8_WAIT_L(n) asm volatile("s_waitcnt lgkmcnt(" #n ")" ::: "memory")
; #define PG8_BAR __builtin_amdgcn_s_barrier()
; #define PG8_SCHED __builtin_amdgcn_sched_barrier(0)
; template <class Epi>
; __device__ __forceinline__ void gemm_phase(LAS unsigned char* lds, const Gemm g, const StaticOrder& S, const Epi& E, const int tid) {
;     ...
;             PG8_LDA(At, 0, 1); PG8_STAGE(PG8_SB(0, 0), b2, voffB); PG8_STAGE(PG8_SB(0, 1), b2 + hstepB, voffB); PG8_STAGE(PG8_SA(0, 0), a2, voffA);
;             PG8_WAIT_V(8); PG8_WAIT_L(0); PG8_BAR; PG8_MMA(1, 0, At, B0); PG8_MMA(1, 1, At, B1); PG8_BAR; PG8_SCHED;
;             PG8_LDB(B0, 1, 0); PG8_LDB(B1, 1, 1); PG8_SCHED; PG8_LDA(At, 1, 0); PG8_STAGE(PG8_SA(0, 1), a2 + hstepA, voffA);
;             PG8_WAIT_V(8); PG8_WAIT_L(0); PG8_BAR; PG8_MMA(0, 0, At, B0); PG8_MMA(0, 1, At, B1); PG8_BAR; PG8_SCHED;
;             PG8_LDA(At, 1, 1); PG8_STAGE(PG8_SB(1, 0), b3, voffB); PG8_STAGE(PG8_SB(1, 1), b3 + hstepB, voffB); PG8_STAGE(PG8_SA(1, 0), a3, voffA);
	s_setprio 1
	s_waitcnt lgkmcnt(0)
	v_mfma_f32_16x16x32_bf16 v[60:63], v[122:125], v[162:165], v[60:63]
	v_mfma_f32_16x16x32_bf16 v[56:59], v[138:141], v[162:165], v[56:59]
	v_mfma_f32_16x16x32_bf16 v[44:47], v[122:125], v[170:173], v[44:47]
	v_mfma_f32_16x16x32_bf16 v[40:43], v[138:141], v[170:173], v[40:43]
	v_mfma_f32_16x16x32_bf16 v[28:31], v[122:125], v[178:181], v[28:31]
	v_mfma_f32_16x16x32_bf16 v[24:27], v[138:141], v[178:181], v[24:27]
	v_mfma_f32_16x16x32_bf16 v[12:15], v[122:125], v[186:189], v[12:15]
	v_mfma_f32_16x16x32_bf16 v[8:11], v[138:141], v[186:189], v[8:11]
	v_mfma_f32_16x16x32_bf16 v[60:63], v[126:129], v[166:169], v[60:63]
	v_mfma_f32_16x16x32_bf16 v[56:59], v[142:145], v[166:169], v[56:59]
	v_mfma_f32_16x16x32_bf16 v[44:47], v[126:129], v[174:177], v[44:47]
	v_mfma_f32_16x16x32_bf16 v[40:43], v[142:145], v[174:177], v[40:43]
	v_mfma_f32_16x16x32_bf16 v[28:31], v[126:129], v[182:185], v[28:31]
	v_mfma_f32_16x16x32_bf16 v[24:27], v[142:145], v[182:185], v[24:27]
	v_mfma_f32_16x16x32_bf16 v[12:15], v[126:129], v[190:193], v[12:15]
	v_mfma_f32_16x16x32_bf16 v[8:11], v[142:145], v[190:193], v[8:11]
	v_mfma_f32_16x16x32_bf16 v[52:55], v[146:149], v[162:165], v[52:55]
	v_mfma_f32_16x16x32_bf16 v[48:51], v[154:157], v[162:165], v[48:51]
	v_mfma_f32_16x16x32_bf16 v[36:39], v[146:149], v[170:173], v[36:39]
	v_mfma_f32_16x16x32_bf16 v[32:35], v[154:157], v[170:173], v[32:35]
	v_mfma_f32_16x16x32_bf16 v[20:23], v[146:149], v[178:181], v[20:23]
	v_mfma_f32_16x16x32_bf16 v[16:19], v[154:157], v[178:181], v[16:19]
	v_mfma_f32_16x16x32_bf16 v[4:7], v[146:149], v[186:189], v[4:7]
	v_mfma_f32_16x16x32_bf16 v[0:3], v[154:157], v[186:189], v[0:3]
	v_mfma_f32_16x16x32_bf16 v[52:55], v[150:153], v[166:169], v[52:55]
	v_mfma_f32_16x16x32_bf16 v[48:51], v[158:161], v[166:169], v[48:51]
	v_mfma_f32_16x16x32_bf16 v[36:39], v[150:153], v[174:177], v[36:39]
	v_mfma_f32_16x16x32_bf16 v[32:35], v[158:161], v[174:177], v[32:35]
	v_mfma_f32_16x16x32_bf16 v[20:23], v[150:153], v[182:185], v[20:23]
	v_mfma_f32_16x16x32_bf16 v[16:19], v[158:161], v[182:185], v[16:19]
	v_mfma_f32_16x16x32_bf16 v[4:7], v[150:153], v[190:193], v[4:7]
	v_mfma_f32_16x16x32_bf16 v[0:3], v[158:161], v[190:193], v[0:3]
	s_setprio 0
	s_barrier
	s_add_i32 s13, 0, 0x18000
	s_add_i32 s31, 0, 0x1c000
	v_add_u32_e32 v142, s13, v245
	v_add_u32_e32 v158, s31, v245
	ds_read_b128 v[122:125], v142
	ds_read_b128 v[126:129], v142 offset:1024
	ds_read_b128 v[138:141], v142 offset:2048
	ds_read_b128 v[142:145], v142 offset:3072
	ds_read_b128 v[146:149], v158
	ds_read_b128 v[150:153], v158 offset:1024
	ds_read_b128 v[154:157], v158 offset:2048
	ds_read_b128 v[158:161], v158 offset:3072
	s_add_u32 s8, vcc_lo, 0xc0000
	s_addc_u32 s9, vcc_hi, 0
	s_mov_b32 m0, s30
	s_nop 0
	ds_read_b128 v[162:165], v246 offset:32768
	ds_read_b128 v[166:169], v246 offset:33792
	ds_read_b128 v[170:173], v246 offset:34816
	ds_read_b128 v[174:177], v246 offset:35840
	ds_read_b128 v[178:181], v246 offset:36864
	ds_read_b128 v[182:185], v246 offset:37888
	ds_read_b128 v[186:189], v246 offset:38912
	ds_read_b128 v[190:193], v246 offset:39936
	global_load_lds_dwordx4 v202, s[8:9]
	v_lshl_add_u64 v[248:249], s[8:9], 0, v[204:205]
	s_mov_b32 m0, s35
	s_nop 0
	global_load_lds_dwordx4 v204, s[8:9]
	s_waitcnt vmcnt(8)
	s_waitcnt lgkmcnt(0)
	s_barrier
	s_setprio 1
	s_waitcnt lgkmcnt(0)
	v_mfma_f32_16x16x32_bf16 v[134:137], v[122:125], v[162:165], v[134:137]
	v_mfma_f32_16x16x32_bf16 v[130:133], v[138:141], v[162:165], v[130:133]
	v_mfma_f32_16x16x32_bf16 v[108:111], v[122:125], v[170:173], v[108:111]
	v_mfma_f32_16x16x32_bf16 v[104:107], v[138:141], v[170:173], v[104:107]
	v_mfma_f32_16x16x32_bf16 v[92:95], v[122:125], v[178:181], v[92:95]
	v_mfma_f32_16x16x32_bf16 v[88:91], v[138:141], v[178:181], v[88:91]
	v_mfma_f32_16x16x32_bf16 v[76:79], v[122:125], v[186:189], v[76:79]
	v_mfma_f32_16x16x32_bf16 v[72:75], v[138:141], v[186:189], v[72:75]
	v_mfma_f32_16x16x32_bf16 v[134:137], v[126:129], v[166:169], v[134:137]
	v_mfma_f32_16x16x32_bf16 v[130:133], v[142:145], v[166:169], v[130:133]
	v_mfma_f32_16x16x32_bf16 v[108:111], v[126:129], v[174:177], v[108:111]
	v_mfma_f32_16x16x32_bf16 v[104:107], v[142:145], v[174:177], v[104:107]
	v_mfma_f32_16x16x32_bf16 v[92:95], v[126:129], v[182:185], v[92:95]
	v_mfma_f32_16x16x32_bf16 v[88:91], v[142:145], v[182:185], v[88:91]
	v_mfma_f32_16x16x32_bf16 v[76:79], v[126:129], v[190:193], v[76:79]
	v_mfma_f32_16x16x32_bf16 v[72:75], v[142:145], v[190:193], v[72:75]
	v_mfma_f32_16x16x32_bf16 v[118:121], v[146:149], v[162:165], v[118:121]
	v_mfma_f32_16x16x32_bf16 v[114:117], v[154:157], v[162:165], v[114:117]
	v_mfma_f32_16x16x32_bf16 v[100:103], v[146:149], v[170:173], v[100:103]
	v_mfma_f32_16x16x32_bf16 v[96:99], v[154:157], v[170:173], v[96:99]
	v_mfma_f32_16x16x32_bf16 v[84:87], v[146:149], v[178:181], v[84:87]
	v_mfma_f32_16x16x32_bf16 v[80:83], v[154:157], v[178:181], v[80:83]
	v_mfma_f32_16x16x32_bf16 v[68:71], v[146:149], v[186:189], v[68:71]
	v_mfma_f32_16x16x32_bf16 v[64:67], v[154:157], v[186:189], v[64:67]
	v_mfma_f32_16x16x32_bf16 v[118:121], v[150:153], v[166:169], v[118:121]
	v_mfma_f32_16x16x32_bf16 v[114:117], v[158:161], v[166:169], v[114:117]
	v_mfma_f32_16x16x32_bf16 v[100:103], v[150:153], v[174:177], v[100:103]
	v_mfma_f32_16x16x32_bf16 v[96:99], v[158:161], v[174:177], v[96:99]
	v_mfma_f32_16x16x32_bf16 v[84:87], v[150:153], v[182:185], v[84:87]
	v_mfma_f32_16x16x32_bf16 v[80:83], v[158:161], v[182:185], v[80:83]
	v_mfma_f32_16x16x32_bf16 v[68:71], v[150:153], v[190:193], v[68:71]
	v_mfma_f32_16x16x32_bf16 v[64:67], v[158:161], v[190:193], v[64:67]
	s_setprio 0
	s_barrier
; #define PG8_STAGE(bufoff, gbase, voff) do { _Pragma("unroll") for (int _i = 0; _i < 2; ++_i) \
;         __builtin_amdgcn_global_load_lds((const unsigned*)((const char*)(gbase) + (voff)[_i]), (LAS unsigned*)(lds + (bufoff) + ldsw + _i * 8192), 16, 0, 0); } while (0)
; #define PG8_LDA(dst, b, h) do { _Pragma("unroll") for (int m = 0; m < 4; ++m) _Pragma("unroll") for (int k = 0; k < 2; ++k) dst[m][k] = *(const LAS bf16x8*)(lds + PG8_SA(b, h) + aoff + m * 2048 + k * 1024); } while (0)
; #define PG8_MMA(ai, bj, At, Bt) do { __builtin_amdgcn_s_setprio(1); _Pragma("unroll") for (int m = 0; m < 4; ++m) _Pragma("unroll") for (int n = 0; n < 2; ++n) _Pragma("unroll") for (int k = 0; k < 2; ++k) \
;         acc[ai][bj][m][n] = __builtin_amdgcn_mfma_f32_16x16x32_bf16(Bt[n][k], At[m][k], acc[ai][bj][m][n], 0, 0, 0); __builtin_amdgcn_s_setprio(0); } while (0)
; #define PG8_WAIT_V(n) asm volatile("s_waitcnt vmcnt(" #n ")" ::: "memory")
; #define PG8_WAIT_L(n) asm volatile("s_waitcnt lgkmcnt(" #n ")" ::: "memory")
; #define PG8_BAR __builtin_amdgcn_s_barrier()
; #define PG8_SCHED __builtin_amdgcn_sched_barrier(0)
; template <class Epi>
; __device__ __forceinline__ void gemm_phase(LAS unsigned char* lds, const Gemm g, const StaticOrder& S, const Epi& E, const int tid) {
;     ...
;             PG8_LDA(At, 1, 1); PG8_STAGE(PG8_SB(1, 0), b3, voffB); PG8_STAGE(PG8_SB(1, 1), b3 + hstepB, voffB); PG8_STAGE(PG8_SA(1, 0), a3, voffA);
;             PG8_WAIT_V(8); PG8_WAIT_L(0); PG8_BAR; PG8_MMA(1, 0, At, B0); PG8_MMA(1, 1, At, B1); PG8_BAR; PG8_SCHED;
;         }
	s_add_i32 s8, s13, s11
	v_lshl_add_u64 v[210:211], v[210:211], 0, s[24:25]
	s_mov_b32 m0, s8
	ds_read_b128 v[162:165], v246 offset:49152
	ds_read_b128 v[166:169], v246 offset:50176
	ds_read_b128 v[170:173], v246 offset:51200
	ds_read_b128 v[174:177], v246 offset:52224
	ds_read_b128 v[178:181], v246 offset:53248
	ds_read_b128 v[182:185], v246 offset:54272
	ds_read_b128 v[186:189], v246 offset:55296
	ds_read_b128 v[190:193], v246 offset:56320
	global_load_lds_dwordx4 v[210:211], off
	s_add_i32 m0, s8, 0x2000
	s_add_u32 s8, s92, 0x40080
	v_lshl_add_u64 v[210:211], v[212:213], 0, s[24:25]
	s_addc_u32 s9, s93, 0
	s_add_i32 s13, s31, s11
	global_load_lds_dwordx4 v[210:211], off
	s_nop 0
	s_mov_b32 m0, s13
	s_nop 0
	global_load_lds_dwordx4 v112, s[8:9]
	s_nop 0
	s_add_i32 m0, s13, 0x2000
	s_nop 0
	global_load_lds_dwordx4 v200, s[8:9]
	v_lshl_add_u64 v[210:211], v[214:215], 0, s[24:25]
	s_mov_b32 m0, s38
	s_nop 0
	global_load_lds_dwordx4 v[210:211], off
	v_lshl_add_u64 v[210:211], v[228:229], 0, s[24:25]
	s_mov_b32 m0, s39
	s_nop 0
	global_load_lds_dwordx4 v[210:211], off
	s_waitcnt vmcnt(8)
	s_waitcnt lgkmcnt(0)
	s_barrier
	s_setprio 1
	s_waitcnt lgkmcnt(0)
	v_mfma_f32_16x16x32_bf16 v[60:63], v[122:125], v[162:165], v[60:63]
	v_mfma_f32_16x16x32_bf16 v[56:59], v[138:141], v[162:165], v[56:59]
	v_mfma_f32_16x16x32_bf16 v[44:47], v[122:125], v[170:173], v[44:47]
	v_mfma_f32_16x16x32_bf16 v[40:43], v[138:141], v[170:173], v[40:43]
	v_mfma_f32_16x16x32_bf16 v[28:31], v[122:125], v[178:181], v[28:31]
	v_mfma_f32_16x16x32_bf16 v[24:27], v[138:141], v[178:181], v[24:27]
	v_mfma_f32_16x16x32_bf16 v[12:15], v[122:125], v[186:189], v[12:15]
	v_mfma_f32_16x16x32_bf16 v[8:11], v[138:141], v[186:189], v[8:11]
	v_mfma_f32_16x16x32_bf16 v[60:63], v[126:129], v[166:169], v[60:63]
	v_mfma_f32_16x16x32_bf16 v[56:59], v[142:145], v[166:169], v[56:59]
	v_mfma_f32_16x16x32_bf16 v[44:47], v[126:129], v[174:177], v[44:47]
	v_mfma_f32_16x16x32_bf16 v[40:43], v[142:145], v[174:177], v[40:43]
	v_mfma_f32_16x16x32_bf16 v[28:31], v[126:129], v[182:185], v[28:31]
	v_mfma_f32_16x16x32_bf16 v[24:27], v[142:145], v[182:185], v[24:27]
	v_mfma_f32_16x16x32_bf16 v[12:15], v[126:129], v[190:193], v[12:15]
	v_mfma_f32_16x16x32_bf16 v[8:11], v[142:145], v[190:193], v[8:11]
	v_mfma_f32_16x16x32_bf16 v[52:55], v[146:149], v[162:165], v[52:55]
	v_mfma_f32_16x16x32_bf16 v[48:51], v[154:157], v[162:165], v[48:51]
	v_mfma_f32_16x16x32_bf16 v[36:39], v[146:149], v[170:173], v[36:39]
	v_mfma_f32_16x16x32_bf16 v[32:35], v[154:157], v[170:173], v[32:35]
	v_mfma_f32_16x16x32_bf16 v[20:23], v[146:149], v[178:181], v[20:23]
	v_mfma_f32_16x16x32_bf16 v[16:19], v[154:157], v[178:181], v[16:19]
	v_mfma_f32_16x16x32_bf16 v[4:7], v[146:149], v[186:189], v[4:7]
	v_mfma_f32_16x16x32_bf16 v[0:3], v[154:157], v[186:189], v[0:3]
	v_mfma_f32_16x16x32_bf16 v[52:55], v[150:153], v[166:169], v[52:55]
	v_mfma_f32_16x16x32_bf16 v[48:51], v[158:161], v[166:169], v[48:51]
	v_mfma_f32_16x16x32_bf16 v[36:39], v[150:153], v[174:177], v[36:39]
	v_mfma_f32_16x16x32_bf16 v[32:35], v[158:161], v[174:177], v[32:35]
	v_mfma_f32_16x16x32_bf16 v[20:23], v[150:153], v[182:185], v[20:23]
	v_mfma_f32_16x16x32_bf16 v[16:19], v[158:161], v[182:185], v[16:19]
	v_mfma_f32_16x16x32_bf16 v[4:7], v[150:153], v[190:193], v[4:7]
	v_mfma_f32_16x16x32_bf16 v[0:3], v[158:161], v[190:193], v[0:3]
	s_setprio 0
	s_barrier
	s_add_i32 s89, s89, 2
	s_add_u32 s45, s45, 0x100
	s_addc_u32 s46, s46, 0
	s_cmp_gt_u32 s89, 13
	s_mov_b64 s[94:95], s[42:43]
	s_cbranch_scc0 .LBB0_160
	s_and_b64 vcc, exec, s[86:87]
	s_cbranch_vccz .LBB0_163
	s_barrier

; #define PG8_STAGE(bufoff, gbase, voff) do { _Pragma("unroll") for (int _i = 0; _i < 2; ++_i) \
;         __builtin_amdgcn_global_load_lds((const unsigned*)((const char*)(gbase) + (voff)[_i]), (LAS unsigned*)(lds + (bufoff) + ldsw + _i * 8192), 16, 0, 0); } while (0)
; #define PG8_LDA(dst, b, h) do { _Pragma("unroll") for (int m = 0; m < 4; ++m) _Pragma("unroll") for (int k = 0; k < 2; ++k) dst[m][k] = *(const LAS bf16x8*)(lds + PG8_SA(b, h) + aoff + m * 2048 + k * 1024); } while (0)
; #define PG8_LDB(dst, b, h) do { _Pragma("unroll") for (int n = 0; n < 2; ++n) _Pragma("unroll") for (int k = 0; k < 2; ++k) dst[n][k] = *(const LAS bf16x8*)(lds + PG8_SB(b, h) + boff + n * 2048 + k * 1024); } while (0)
; #define PG8_MMA(ai, bj, At, Bt) do { __builtin_amdgcn_s_setprio(1); _Pragma("unroll") for (int m = 0; m < 4; ++m) _Pragma("unroll") for (int n = 0; n < 2; ++n) _Pragma("unroll") for (int k = 0; k < 2; ++k) \
;         acc[ai][bj][m][n] = __builtin_amdgcn_mfma_f32_16x16x32_bf16(Bt[n][k], At[m][k], acc[ai][bj][m][n], 0, 0, 0); __builtin_amdgcn_s_setprio(0); } while (0)
; #define PG8_WAIT_V(n) asm volatile("s_waitcnt vmcnt(" #n ")" ::: "memory")
; #define PG8_WAIT_L(n) asm volatile("s_waitcnt lgkmcnt(" #n ")" ::: "memory")
; #define PG8_BAR __builtin_amdgcn_s_barrier()
; #define PG8_SCHED __builtin_amdgcn_sched_barrier(0)
; template <class Epi>
; __device__ __forceinline__ void gemm_phase(LAS unsigned char* lds, const Gemm g, const StaticOrder& S, const Epi& E, const int tid) {
;     ...
;         for (int t = 0; t < nt; t += 2) {
;             const bool last = (t == nt - 2);
;             const char* a1 = cA + (size_t)(t + 1) * kstep + ((t + 1) >= 8 ? xtra : 0);
;             const char* a2 = last ? nA : cA + (size_t)(t + 2) * kstep + ((t + 2) >= 8 ? xtra : 0); const char* b2 = last ? nB : cB + (size_t)(t + 2) * kstep;
;             const char* a3 = a2 + kstep; const char* b3 = b2 + kstep;
;             PG8_LDB(B0, 0, 0); PG8_LDB(B1, 0, 1); PG8_SCHED; PG8_LDA(At, 0, 0); PG8_STAGE(PG8_SA(1, 1), a1 + hstepA, voffA);
;             PG8_WAIT_V(8); PG8_WAIT_L(0); PG8_BAR; PG8_MMA(0, 0, At, B0); PG8_MMA(0, 1, At, B1); PG8_BAR; PG8_SCHED;
;             PG8_LDA(At, 0, 1); PG8_STAGE(PG8_SB(0, 0), b2, voffB); PG8_STAGE(PG8_SB(0, 1), b2 + hstepB, voffB); PG8_STAGE(PG8_SA(0, 0), a2, voffA);
.LBB0_230:
	s_add_i32 s96, s40, 2
	s_cmp_gt_u32 s96, 7
	s_cselect_b32 s46, 0x600, 0
	s_cmp_gt_u32 s96, 5
	s_cselect_b32 s8, 0x600, 0
	s_add_u32 s8, s88, s8
	s_addc_u32 s9, s89, 0
	s_add_u32 s8, s8, 0x100
	s_addc_u32 s9, s9, 0
	s_add_i32 s13, 0, 0x10000
	v_add_u32_e32 v142, s13, v210
	v_add_u32_e32 v158, s15, v210
	ds_read_b128 v[130:133], v142
	ds_read_b128 v[134:137], v142 offset:1024
	ds_read_b128 v[138:141], v142 offset:2048
	ds_read_b128 v[142:145], v142 offset:3072
	ds_read_b128 v[146:149], v158
	ds_read_b128 v[150:153], v158 offset:1024
	ds_read_b128 v[154:157], v158 offset:2048
	ds_read_b128 v[158:161], v158 offset:3072
	s_cmp_eq_u32 s40, 12
	s_cselect_b32 s40, s87, vcc_lo
	s_cselect_b32 s91, s83, s9
	s_cselect_b32 s90, s82, s8
	s_cselect_b32 s41, s81, vcc_hi
	v_lshl_add_u64 v[212:213], s[88:89], 0, v[190:191]
	v_lshl_add_u64 v[212:213], v[212:213], 0, s[46:47]
	s_add_i32 m0, s19, 0xc000
	ds_read_b128 v[162:165], v211
	ds_read_b128 v[166:169], v211 offset:1024
	ds_read_b128 v[170:173], v211 offset:2048
	ds_read_b128 v[174:177], v211 offset:3072
	ds_read_b128 v[178:181], v211 offset:4096
	ds_read_b128 v[182:185], v211 offset:5120
	ds_read_b128 v[202:205], v211 offset:6144
	ds_read_b128 v[206:209], v211 offset:7168
	global_load_lds_dwordx4 v[212:213], off
	v_lshl_add_u64 v[212:213], s[88:89], 0, v[192:193]
	v_lshl_add_u64 v[212:213], v[212:213], 0, s[46:47]
	s_add_i32 m0, s19, 0xe000
	s_nop 0
	global_load_lds_dwordx4 v[212:213], off
	s_waitcnt vmcnt(8)
	s_waitcnt lgkmcnt(0)
	s_barrier
	s_setprio 1
	s_waitcnt lgkmcnt(0)
	v_mfma_f32_16x16x32_bf16 v[126:129], v[130:133], v[162:165], v[126:129]
	v_mfma_f32_16x16x32_bf16 v[122:125], v[138:141], v[162:165], v[122:125]
	v_mfma_f32_16x16x32_bf16 v[108:111], v[130:133], v[170:173], v[108:111]
	v_mfma_f32_16x16x32_bf16 v[104:107], v[138:141], v[170:173], v[104:107]
	v_mfma_f32_16x16x32_bf16 v[92:95], v[130:133], v[178:181], v[92:95]
	v_mfma_f32_16x16x32_bf16 v[88:91], v[138:141], v[178:181], v[88:91]
	v_mfma_f32_16x16x32_bf16 v[76:79], v[130:133], v[202:205], v[76:79]
	v_mfma_f32_16x16x32_bf16 v[72:75], v[138:141], v[202:205], v[72:75]
	v_mfma_f32_16x16x32_bf16 v[126:129], v[134:137], v[166:169], v[126:129]
	v_mfma_f32_16x16x32_bf16 v[122:125], v[142:145], v[166:169], v[122:125]
	v_mfma_f32_16x16x32_bf16 v[108:111], v[134:137], v[174:177], v[108:111]
	v_mfma_f32_16x16x32_bf16 v[104:107], v[142:145], v[174:177], v[104:107]
	v_mfma_f32_16x16x32_bf16 v[92:95], v[134:137], v[182:185], v[92:95]
	v_mfma_f32_16x16x32_bf16 v[88:91], v[142:145], v[182:185], v[88:91]
	v_mfma_f32_16x16x32_bf16 v[76:79], v[134:137], v[206:209], v[76:79]
	v_mfma_f32_16x16x32_bf16 v[72:75], v[142:145], v[206:209], v[72:75]
	v_mfma_f32_16x16x32_bf16 v[118:121], v[146:149], v[162:165], v[118:121]
	v_mfma_f32_16x16x32_bf16 v[114:117], v[154:157], v[162:165], v[114:117]
	v_mfma_f32_16x16x32_bf16 v[100:103], v[146:149], v[170:173], v[100:103]
	v_mfma_f32_16x16x32_bf16 v[96:99], v[154:157], v[170:173], v[96:99]
	v_mfma_f32_16x16x32_bf16 v[84:87], v[146:149], v[178:181], v[84:87]
	v_mfma_f32_16x16x32_bf16 v[80:83], v[154:157], v[178:181], v[80:83]
	v_mfma_f32_16x16x32_bf16 v[68:71], v[146:149], v[202:205], v[68:71]
	v_mfma_f32_16x16x32_bf16 v[64:67], v[154:157], v[202:205], v[64:67]
	v_mfma_f32_16x16x32_bf16 v[118:121], v[150:153], v[166:169], v[118:121]
	v_mfma_f32_16x16x32_bf16 v[114:117], v[158:161], v[166:169], v[114:117]
	v_mfma_f32_16x16x32_bf16 v[100:103], v[150:153], v[174:177], v[100:103]
	v_mfma_f32_16x16x32_bf16 v[96:99], v[158:161], v[174:177], v[96:99]
	v_mfma_f32_16x16x32_bf16 v[84:87], v[150:153], v[182:185], v[84:87]
	v_mfma_f32_16x16x32_bf16 v[80:83], v[158:161], v[182:185], v[80:83]
	v_mfma_f32_16x16x32_bf16 v[68:71], v[150:153], v[206:209], v[68:71]
	v_mfma_f32_16x16x32_bf16 v[64:67], v[158:161], v[206:209], v[64:67]
	s_setprio 0
	s_barrier
	s_add_i32 s8, s13, s11
	v_lshl_add_u64 v[212:213], s[40:41], 0, v[112:113]
	s_mov_b32 m0, s8
	ds_read_b128 v[162:165], v211 offset:16384
	ds_read_b128 v[166:169], v211 offset:17408
	ds_read_b128 v[170:173], v211 offset:18432
	ds_read_b128 v[174:177], v211 offset:19456
	ds_read_b128 v[178:181], v211 offset:20480
	ds_read_b128 v[182:185], v211 offset:21504
	ds_read_b128 v[202:205], v211 offset:22528
	ds_read_b128 v[206:209], v211 offset:23552
	global_load_lds_dwordx4 v112, s[40:41]
	s_add_i32 m0, s8, 0x2000
	s_add_u32 s8, s40, 0x40000
	v_lshl_add_u64 v[214:215], s[40:41], 0, v[200:201]
	s_addc_u32 s9, s41, 0
	s_add_i32 s13, s15, s11
	global_load_lds_dwordx4 v200, s[40:41]
	s_nop 0
	s_mov_b32 m0, s13
	v_lshl_add_u64 v[236:237], s[90:91], 0, v[188:189]
	global_load_lds_dwordx4 v112, s[8:9]
	s_nop 0
	s_add_i32 m0, s13, 0x2000
	s_nop 0
	global_load_lds_dwordx4 v200, s[8:9]
	v_lshl_add_u64 v[228:229], s[90:91], 0, v[186:187]
	s_mov_b32 m0, s19
	s_nop 0
	global_load_lds_dwordx4 v186, s[90:91]
	s_mov_b32 m0, s23
	s_nop 0
	global_load_lds_dwordx4 v188, s[90:91]
	s_waitcnt vmcnt(8)
	s_waitcnt lgkmcnt(0)
	s_barrier
; #define PG8_STAGE(bufoff, gbase, voff) do { _Pragma("unroll") for (int _i = 0; _i < 2; ++_i) \
;         __builtin_amdgcn_global_load_lds((const unsigned*)((const char*)(gbase) + (voff)[_i]), (LAS unsigned*)(lds + (bufoff) + ldsw + _i * 8192), 16, 0, 0); } while (0)
; #define PG8_LDA(dst, b, h) do { _Pragma("unroll") for (int m = 0; m < 4; ++m) _Pragma("unroll") for (int k = 0; k < 2; ++k) dst[m][k] = *(const LAS bf16x8*)(lds + PG8_SA(b, h) + aoff + m * 2048 + k * 1024); } while (0)
; #define PG8_LDB(dst, b, h) do { _Pragma("unroll") for (int n = 0; n < 2; ++n) _Pragma("unroll") for (int k = 0; k < 2; ++k) dst[n][k] = *(const LAS bf16x8*)(lds + PG8_SB(b, h) + boff + n * 2048 + k * 1024); } while (0)
; #define PG8_MMA(ai, bj, At, Bt) do { __builtin_amdgcn_s_setprio(1); _Pragma("unroll") for (int m = 0; m < 4; ++m) _Pragma("unroll") for (int n = 0; n < 2; ++n) _Pragma("unroll") for (int k = 0; k < 2; ++k) \
;         acc[ai][bj][m][n] = __builtin_amdgcn_mfma_f32_16x16x32_bf16(Bt[n][k], At[m][k], acc[ai][bj][m][n], 0, 0, 0); __builtin_amdgcn_s_setprio(0); } while (0)
; #define PG8_WAIT_V(n) asm volatile("s_waitcnt vmcnt(" #n ")" ::: "memory")
; #define PG8_WAIT_L(n) asm volatile("s_waitcnt lgkmcnt(" #n ")" ::: "memory")
; #define PG8_BAR __builtin_amdgcn_s_barrier()
; #define PG8_SCHED __builtin_amdgcn_sched_barrier(0)
; template <class Epi>
; __device__ __forceinline__ void gemm_phase(LAS unsigned char* lds, const Gemm g, const StaticOrder& S, const Epi& E, const int tid) {
;     ...
;             PG8_LDA(At, 0, 1); PG8_STAGE(PG8_SB(0, 0), b2, voffB); PG8_STAGE(PG8_SB(0, 1), b2 + hstepB, voffB); PG8_STAGE(PG8_SA(0, 0), a2, voffA);
;             PG8_WAIT_V(8); PG8_WAIT_L(0); PG8_BAR; PG8_MMA(1, 0, At, B0); PG8_MMA(1, 1, At, B1); PG8_BAR; PG8_SCHED;
;             PG8_LDB(B0, 1, 0); PG8_LDB(B1, 1, 1); PG8_SCHED; PG8_LDA(At, 1, 0); PG8_STAGE(PG8_SA(0, 1), a2 + hstepA, voffA);
;             PG8_WAIT_V(8); PG8_WAIT_L(0); PG8_BAR; PG8_MMA(0, 0, At, B0); PG8_MMA(0, 1, At, B1); PG8_BAR; PG8_SCHED;
;             PG8_LDA(At, 1, 1); PG8_STAGE(PG8_SB(1, 0), b3, voffB); PG8_STAGE(PG8_SB(1, 1), b3 + hstepB, voffB); PG8_STAGE(PG8_SA(1, 0), a3, voffA);
	s_setprio 1
	s_waitcnt lgkmcnt(0)
	v_mfma_f32_16x16x32_bf16 v[60:63], v[130:133], v[162:165], v[60:63]
	v_mfma_f32_16x16x32_bf16 v[56:59], v[138:141], v[162:165], v[56:59]
	v_mfma_f32_16x16x32_bf16 v[44:47], v[130:133], v[170:173], v[44:47]
	v_mfma_f32_16x16x32_bf16 v[40:43], v[138:141], v[170:173], v[40:43]
	v_mfma_f32_16x16x32_bf16 v[28:31], v[130:133], v[178:181], v[28:31]
	v_mfma_f32_16x16x32_bf16 v[24:27], v[138:141], v[178:181], v[24:27]
	v_mfma_f32_16x16x32_bf16 v[12:15], v[130:133], v[202:205], v[12:15]
	v_mfma_f32_16x16x32_bf16 v[8:11], v[138:141], v[202:205], v[8:11]
	v_mfma_f32_16x16x32_bf16 v[60:63], v[134:137], v[166:169], v[60:63]
	v_mfma_f32_16x16x32_bf16 v[56:59], v[142:145], v[166:169], v[56:59]
	v_mfma_f32_16x16x32_bf16 v[44:47], v[134:137], v[174:177], v[44:47]
	v_mfma_f32_16x16x32_bf16 v[40:43], v[142:145], v[174:177], v[40:43]
	v_mfma_f32_16x16x32_bf16 v[28:31], v[134:137], v[182:185], v[28:31]
	v_mfma_f32_16x16x32_bf16 v[24:27], v[142:145], v[182:185], v[24:27]
	v_mfma_f32_16x16x32_bf16 v[12:15], v[134:137], v[206:209], v[12:15]
	v_mfma_f32_16x16x32_bf16 v[8:11], v[142:145], v[206:209], v[8:11]
	v_mfma_f32_16x16x32_bf16 v[52:55], v[146:149], v[162:165], v[52:55]
	v_mfma_f32_16x16x32_bf16 v[48:51], v[154:157], v[162:165], v[48:51]
	v_mfma_f32_16x16x32_bf16 v[36:39], v[146:149], v[170:173], v[36:39]
	v_mfma_f32_16x16x32_bf16 v[32:35], v[154:157], v[170:173], v[32:35]
	v_mfma_f32_16x16x32_bf16 v[20:23], v[146:149], v[178:181], v[20:23]
	v_mfma_f32_16x16x32_bf16 v[16:19], v[154:157], v[178:181], v[16:19]
	v_mfma_f32_16x16x32_bf16 v[4:7], v[146:149], v[202:205], v[4:7]
	v_mfma_f32_16x16x32_bf16 v[0:3], v[154:157], v[202:205], v[0:3]
	v_mfma_f32_16x16x32_bf16 v[52:55], v[150:153], v[166:169], v[52:55]
	v_mfma_f32_16x16x32_bf16 v[48:51], v[158:161], v[166:169], v[48:51]
	v_mfma_f32_16x16x32_bf16 v[36:39], v[150:153], v[174:177], v[36:39]
	v_mfma_f32_16x16x32_bf16 v[32:35], v[158:161], v[174:177], v[32:35]
	v_mfma_f32_16x16x32_bf16 v[20:23], v[150:153], v[182:185], v[20:23]
	v_mfma_f32_16x16x32_bf16 v[16:19], v[158:161], v[182:185], v[16:19]
	v_mfma_f32_16x16x32_bf16 v[4:7], v[150:153], v[206:209], v[4:7]
	v_mfma_f32_16x16x32_bf16 v[0:3], v[158:161], v[206:209], v[0:3]
	s_setprio 0
	s_barrier
	s_add_i32 s13, 0, 0x18000
	s_add_i32 s31, 0, 0x1c000
	v_add_u32_e32 v142, s13, v210
	v_add_u32_e32 v158, s31, v210
	ds_read_b128 v[130:133], v142
	ds_read_b128 v[134:137], v142 offset:1024
	ds_read_b128 v[138:141], v142 offset:2048
	ds_read_b128 v[142:145], v142 offset:3072
	ds_read_b128 v[146:149], v158
	ds_read_b128 v[150:153], v158 offset:1024
	ds_read_b128 v[154:157], v158 offset:2048
	ds_read_b128 v[158:161], v158 offset:3072
	s_add_u32 s8, s90, 0x90000
	s_addc_u32 s9, s91, 0
	s_mov_b32 m0, s28
	s_nop 0
	ds_read_b128 v[162:165], v211 offset:32768
	ds_read_b128 v[166:169], v211 offset:33792
	ds_read_b128 v[170:173], v211 offset:34816
	ds_read_b128 v[174:177], v211 offset:35840
	ds_read_b128 v[178:181], v211 offset:36864
	ds_read_b128 v[182:185], v211 offset:37888
	ds_read_b128 v[202:205], v211 offset:38912
	ds_read_b128 v[206:209], v211 offset:39936
	global_load_lds_dwordx4 v186, s[8:9]
	v_lshl_add_u64 v[238:239], s[8:9], 0, v[188:189]
	s_mov_b32 m0, s30
	s_nop 0
	global_load_lds_dwordx4 v188, s[8:9]
	s_waitcnt vmcnt(8)
	s_waitcnt lgkmcnt(0)
	s_barrier
	s_setprio 1
	s_waitcnt lgkmcnt(0)
	v_mfma_f32_16x16x32_bf16 v[126:129], v[130:133], v[162:165], v[126:129]
	v_mfma_f32_16x16x32_bf16 v[122:125], v[138:141], v[162:165], v[122:125]
	v_mfma_f32_16x16x32_bf16 v[108:111], v[130:133], v[170:173], v[108:111]
	v_mfma_f32_16x16x32_bf16 v[104:107], v[138:141], v[170:173], v[104:107]
	v_mfma_f32_16x16x32_bf16 v[92:95], v[130:133], v[178:181], v[92:95]
	v_mfma_f32_16x16x32_bf16 v[88:91], v[138:141], v[178:181], v[88:91]
	v_mfma_f32_16x16x32_bf16 v[76:79], v[130:133], v[202:205], v[76:79]
	v_mfma_f32_16x16x32_bf16 v[72:75], v[138:141], v[202:205], v[72:75]
	v_mfma_f32_16x16x32_bf16 v[126:129], v[134:137], v[166:169], v[126:129]
	v_mfma_f32_16x16x32_bf16 v[122:125], v[142:145], v[166:169], v[122:125]
	v_mfma_f32_16x16x32_bf16 v[108:111], v[134:137], v[174:177], v[108:111]
	v_mfma_f32_16x16x32_bf16 v[104:107], v[142:145], v[174:177], v[104:107]
	v_mfma_f32_16x16x32_bf16 v[92:95], v[134:137], v[182:185], v[92:95]
	v_mfma_f32_16x16x32_bf16 v[88:91], v[142:145], v[182:185], v[88:91]
	v_mfma_f32_16x16x32_bf16 v[76:79], v[134:137], v[206:209], v[76:79]
	v_mfma_f32_16x16x32_bf16 v[72:75], v[142:145], v[206:209], v[72:75]
	v_mfma_f32_16x16x32_bf16 v[118:121], v[146:149], v[162:165], v[118:121]
	v_mfma_f32_16x16x32_bf16 v[114:117], v[154:157], v[162:165], v[114:117]
	v_mfma_f32_16x16x32_bf16 v[100:103], v[146:149], v[170:173], v[100:103]
	v_mfma_f32_16x16x32_bf16 v[96:99], v[154:157], v[170:173], v[96:99]
	v_mfma_f32_16x16x32_bf16 v[84:87], v[146:149], v[178:181], v[84:87]
	v_mfma_f32_16x16x32_bf16 v[80:83], v[154:157], v[178:181], v[80:83]
	v_mfma_f32_16x16x32_bf16 v[68:71], v[146:149], v[202:205], v[68:71]
	v_mfma_f32_16x16x32_bf16 v[64:67], v[154:157], v[202:205], v[64:67]
	v_mfma_f32_16x16x32_bf16 v[118:121], v[150:153], v[166:169], v[118:121]
	v_mfma_f32_16x16x32_bf16 v[114:117], v[158:161], v[166:169], v[114:117]
	v_mfma_f32_16x16x32_bf16 v[100:103], v[150:153], v[174:177], v[100:103]
	v_mfma_f32_16x16x32_bf16 v[96:99], v[158:161], v[174:177], v[96:99]
	v_mfma_f32_16x16x32_bf16 v[84:87], v[150:153], v[182:185], v[84:87]
	v_mfma_f32_16x16x32_bf16 v[80:83], v[158:161], v[182:185], v[80:83]
	v_mfma_f32_16x16x32_bf16 v[68:71], v[150:153], v[206:209], v[68:71]
	v_mfma_f32_16x16x32_bf16 v[64:67], v[158:161], v[206:209], v[64:67]
	s_setprio 0
	s_barrier
; #define PG8_STAGE(bufoff, gbase, voff) do { _Pragma("unroll") for (int _i = 0; _i < 2; ++_i) \
;         __builtin_amdgcn_global_load_lds((const unsigned*)((const char*)(gbase) + (voff)[_i]), (LAS unsigned*)(lds + (bufoff) + ldsw + _i * 8192), 16, 0, 0); } while (0)
; #define PG8_LDA(dst, b, h) do { _Pragma("unroll") for (int m = 0; m < 4; ++m) _Pragma("unroll") for (int k = 0; k < 2; ++k) dst[m][k] = *(const LAS bf16x8*)(lds + PG8_SA(b, h) + aoff + m * 2048 + k * 1024); } while (0)
; #define PG8_MMA(ai, bj, At, Bt) do { __builtin_amdgcn_s_setprio(1); _Pragma("unroll") for (int m = 0; m < 4; ++m) _Pragma("unroll") for (int n = 0; n < 2; ++n) _Pragma("unroll") for (int k = 0; k < 2; ++k) \
;         acc[ai][bj][m][n] = __builtin_amdgcn_mfma_f32_16x16x32_bf16(Bt[n][k], At[m][k], acc[ai][bj][m][n], 0, 0, 0); __builtin_amdgcn_s_setprio(0); } while (0)
; #define PG8_WAIT_V(n) asm volatile("s_waitcnt vmcnt(" #n ")" ::: "memory")
; #define PG8_WAIT_L(n) asm volatile("s_waitcnt lgkmcnt(" #n ")" ::: "memory")
; #define PG8_BAR __builtin_amdgcn_s_barrier()
; #define PG8_SCHED __builtin_amdgcn_sched_barrier(0)
; template <class Epi>
; __device__ __forceinline__ void gemm_phase(LAS unsigned char* lds, const Gemm g, const StaticOrder& S, const Epi& E, const int tid) {
;     ...
;             PG8_LDA(At, 1, 1); PG8_STAGE(PG8_SB(1, 0), b3, voffB); PG8_STAGE(PG8_SB(1, 1), b3 + hstepB, voffB); PG8_STAGE(PG8_SA(1, 0), a3, voffA);
;             PG8_WAIT_V(8); PG8_WAIT_L(0); PG8_BAR; PG8_MMA(1, 0, At, B0); PG8_MMA(1, 1, At, B1); PG8_BAR; PG8_SCHED;
;         }
	s_add_i32 s8, s13, s11
	v_lshl_add_u64 v[212:213], v[212:213], 0, s[24:25]
	s_mov_b32 m0, s8
	ds_read_b128 v[162:165], v211 offset:49152
	ds_read_b128 v[166:169], v211 offset:50176
	ds_read_b128 v[170:173], v211 offset:51200
	ds_read_b128 v[174:177], v211 offset:52224
	ds_read_b128 v[178:181], v211 offset:53248
	ds_read_b128 v[182:185], v211 offset:54272
	ds_read_b128 v[202:205], v211 offset:55296
	ds_read_b128 v[206:209], v211 offset:56320
	global_load_lds_dwordx4 v[212:213], off
	s_add_i32 m0, s8, 0x2000
	s_add_u32 s8, s40, 0x40080
	v_lshl_add_u64 v[212:213], v[214:215], 0, s[24:25]
	s_addc_u32 s9, s41, 0
	s_add_i32 s13, s31, s11
	global_load_lds_dwordx4 v[212:213], off
	s_nop 0
	s_mov_b32 m0, s13
	s_nop 0
	global_load_lds_dwordx4 v112, s[8:9]
	s_nop 0
	s_add_i32 m0, s13, 0x2000
	s_nop 0
	global_load_lds_dwordx4 v200, s[8:9]
	v_lshl_add_u64 v[212:213], v[228:229], 0, s[24:25]
	s_mov_b32 m0, s99
	s_nop 0
	global_load_lds_dwordx4 v[212:213], off
	v_lshl_add_u64 v[212:213], v[236:237], 0, s[24:25]
	s_mov_b32 m0, s33
	s_nop 0
	global_load_lds_dwordx4 v[212:213], off
	s_waitcnt vmcnt(8)
	s_waitcnt lgkmcnt(0)
	s_barrier
	s_setprio 1
	s_waitcnt lgkmcnt(0)
	v_mfma_f32_16x16x32_bf16 v[60:63], v[130:133], v[162:165], v[60:63]
	v_mfma_f32_16x16x32_bf16 v[56:59], v[138:141], v[162:165], v[56:59]
	v_mfma_f32_16x16x32_bf16 v[44:47], v[130:133], v[170:173], v[44:47]
	v_mfma_f32_16x16x32_bf16 v[40:43], v[138:141], v[170:173], v[40:43]
	v_mfma_f32_16x16x32_bf16 v[28:31], v[130:133], v[178:181], v[28:31]
	v_mfma_f32_16x16x32_bf16 v[24:27], v[138:141], v[178:181], v[24:27]
	v_mfma_f32_16x16x32_bf16 v[12:15], v[130:133], v[202:205], v[12:15]
	v_mfma_f32_16x16x32_bf16 v[8:11], v[138:141], v[202:205], v[8:11]
	v_mfma_f32_16x16x32_bf16 v[60:63], v[134:137], v[166:169], v[60:63]
	v_mfma_f32_16x16x32_bf16 v[56:59], v[142:145], v[166:169], v[56:59]
	v_mfma_f32_16x16x32_bf16 v[44:47], v[134:137], v[174:177], v[44:47]
	v_mfma_f32_16x16x32_bf16 v[40:43], v[142:145], v[174:177], v[40:43]
	v_mfma_f32_16x16x32_bf16 v[28:31], v[134:137], v[182:185], v[28:31]
	v_mfma_f32_16x16x32_bf16 v[24:27], v[142:145], v[182:185], v[24:27]
	v_mfma_f32_16x16x32_bf16 v[12:15], v[134:137], v[206:209], v[12:15]
	v_mfma_f32_16x16x32_bf16 v[8:11], v[142:145], v[206:209], v[8:11]
	v_mfma_f32_16x16x32_bf16 v[52:55], v[146:149], v[162:165], v[52:55]
	v_mfma_f32_16x16x32_bf16 v[48:51], v[154:157], v[162:165], v[48:51]
	v_mfma_f32_16x16x32_bf16 v[36:39], v[146:149], v[170:173], v[36:39]
	v_mfma_f32_16x16x32_bf16 v[32:35], v[154:157], v[170:173], v[32:35]
	v_mfma_f32_16x16x32_bf16 v[20:23], v[146:149], v[178:181], v[20:23]
	v_mfma_f32_16x16x32_bf16 v[16:19], v[154:157], v[178:181], v[16:19]
	v_mfma_f32_16x16x32_bf16 v[4:7], v[146:149], v[202:205], v[4:7]
	v_mfma_f32_16x16x32_bf16 v[0:3], v[154:157], v[202:205], v[0:3]
	v_mfma_f32_16x16x32_bf16 v[52:55], v[150:153], v[166:169], v[52:55]
	v_mfma_f32_16x16x32_bf16 v[48:51], v[158:161], v[166:169], v[48:51]
	v_mfma_f32_16x16x32_bf16 v[36:39], v[150:153], v[174:177], v[36:39]
	v_mfma_f32_16x16x32_bf16 v[32:35], v[158:161], v[174:177], v[32:35]
	v_mfma_f32_16x16x32_bf16 v[20:23], v[150:153], v[182:185], v[20:23]
	v_mfma_f32_16x16x32_bf16 v[16:19], v[158:161], v[182:185], v[16:19]
	v_mfma_f32_16x16x32_bf16 v[4:7], v[150:153], v[206:209], v[4:7]
	v_mfma_f32_16x16x32_bf16 v[0:3], v[158:161], v[206:209], v[0:3]
	s_setprio 0
	s_barrier
	s_add_u32 s88, s88, 0x100
	s_addc_u32 s89, s89, 0
	s_add_u32 vcc_lo, vcc_lo, 0x100
	s_addc_u32 vcc_hi, vcc_hi, 0
	s_cmp_gt_u32 s96, 13
	s_mov_b32 s40, s96
	s_cbranch_scc0 .LBB0_230
	s_and_b64 vcc, exec, s[44:45]
	s_cbranch_vccz .LBB0_233
	s_barrier

; #define PG8_STAGE(bufoff, gbase, voff) do { _Pragma("unroll") for (int _i = 0; _i < 2; ++_i) \
;         __builtin_amdgcn_global_load_lds((const unsigned*)((const char*)(gbase) + (voff)[_i]), (LAS unsigned*)(lds + (bufoff) + ldsw + _i * 8192), 16, 0, 0); } while (0)
; #define PG8_LDA(dst, b, h) do { _Pragma("unroll") for (int m = 0; m < 4; ++m) _Pragma("unroll") for (int k = 0; k < 2; ++k) dst[m][k] = *(const LAS bf16x8*)(lds + PG8_SA(b, h) + aoff + m * 2048 + k * 1024); } while (0)
; #define PG8_LDB(dst, b, h) do { _Pragma("unroll") for (int n = 0; n < 2; ++n) _Pragma("unroll") for (int k = 0; k < 2; ++k) dst[n][k] = *(const LAS bf16x8*)(lds + PG8_SB(b, h) + boff + n * 2048 + k * 1024); } while (0)
; #define PG8_MMA(ai, bj, At, Bt) do { __builtin_amdgcn_s_setprio(1); _Pragma("unroll") for (int m = 0; m < 4; ++m) _Pragma("unroll") for (int n = 0; n < 2; ++n) _Pragma("unroll") for (int k = 0; k < 2; ++k) \
;         acc[ai][bj][m][n] = __builtin_amdgcn_mfma_f32_16x16x32_bf16(Bt[n][k], At[m][k], acc[ai][bj][m][n], 0, 0, 0); __builtin_amdgcn_s_setprio(0); } while (0)
; #define PG8_WAIT_V(n) asm volatile("s_waitcnt vmcnt(" #n ")" ::: "memory")
; #define PG8_WAIT_L(n) asm volatile("s_waitcnt lgkmcnt(" #n ")" ::: "memory")
; #define PG8_BAR __builtin_amdgcn_s_barrier()
; #define PG8_SCHED __builtin_amdgcn_sched_barrier(0)
; template <class Epi>
; __device__ __forceinline__ void gemm_phase(LAS unsigned char* lds, const Gemm g, const StaticOrder& S, const Epi& E, const int tid) {
;     ...
;         for (int t = 0; t < nt; t += 2) {
;             const bool last = (t == nt - 2);
;             const char* a1 = cA + (size_t)(t + 1) * kstep + ((t + 1) >= 8 ? xtra : 0);
;             const char* a2 = last ? nA : cA + (size_t)(t + 2) * kstep + ((t + 2) >= 8 ? xtra : 0); const char* b2 = last ? nB : cB + (size_t)(t + 2) * kstep;
;             const char* a3 = a2 + kstep; const char* b3 = b2 + kstep;
;             PG8_LDB(B0, 0, 0); PG8_LDB(B1, 0, 1); PG8_SCHED; PG8_LDA(At, 0, 0); PG8_STAGE(PG8_SA(1, 1), a1 + hstepA, voffA);
;             PG8_WAIT_V(8); PG8_WAIT_L(0); PG8_BAR; PG8_MMA(0, 0, At, B0); PG8_MMA(0, 1, At, B1); PG8_BAR; PG8_SCHED;
;             PG8_LDA(At, 0, 1); PG8_STAGE(PG8_SB(0, 0), b2, voffB); PG8_STAGE(PG8_SB(0, 1), b2 + hstepB, voffB); PG8_STAGE(PG8_SA(0, 0), a2, voffA);
.LBB0_268:
	s_add_u32 s8, s40, 0xfffc0080
	s_addc_u32 s9, s41, -1
	s_add_i32 s13, 0, 0x10000
	v_add_u32_e32 v162, s13, v167
	ds_read_b128 v[150:153], v162
	ds_read_b128 v[154:157], v162 offset:1024
	ds_read_b128 v[158:161], v162 offset:2048
	ds_read_b128 v[170:173], v162 offset:3072
	v_add_u32_e32 v162, s15, v167
	ds_read_b128 v[174:177], v162
	ds_read_b128 v[178:181], v162 offset:1024
	ds_read_b128 v[182:185], v162 offset:2048
	ds_read_b128 v[186:189], v162 offset:3072
	s_cmp_eq_u32 s85, 12
	s_cselect_b32 vcc_hi, s33, s9
	s_cselect_b32 vcc_lo, s36, s8
	s_cselect_b32 s95, s37, s57
	s_cselect_b32 s94, s45, s46
	s_nop 0
	s_add_i32 m0, s11, 0xc000
	ds_read_b128 v[190:193], v169
	ds_read_b128 v[200:203], v169 offset:1024
	ds_read_b128 v[204:207], v169 offset:2048
	ds_read_b128 v[208:211], v169 offset:3072
	ds_read_b128 v[212:215], v169 offset:4096
	ds_read_b128 v[234:237], v169 offset:5120
	ds_read_b128 v[238:241], v169 offset:6144
	ds_read_b128 v[242:245], v169 offset:7168
	global_load_lds_dwordx4 v146, s[40:41]
	s_nop 0
	s_add_i32 m0, s11, 0xe000
	s_nop 0
	global_load_lds_dwordx4 v148, s[40:41]
	s_waitcnt vmcnt(8)
	s_waitcnt lgkmcnt(0)
	s_barrier
	s_setprio 1
	s_waitcnt lgkmcnt(0)
	v_mfma_f32_16x16x32_bf16 v[134:137], v[150:153], v[190:193], v[134:137]
	v_mfma_f32_16x16x32_bf16 v[130:133], v[158:161], v[190:193], v[130:133]
	v_mfma_f32_16x16x32_bf16 v[118:121], v[150:153], v[204:207], v[118:121]
	v_mfma_f32_16x16x32_bf16 v[114:117], v[158:161], v[204:207], v[114:117]
	v_mfma_f32_16x16x32_bf16 v[100:103], v[150:153], v[212:215], v[100:103]
	v_mfma_f32_16x16x32_bf16 v[96:99], v[158:161], v[212:215], v[96:99]
	v_mfma_f32_16x16x32_bf16 v[84:87], v[150:153], v[238:241], v[84:87]
	v_mfma_f32_16x16x32_bf16 v[80:83], v[158:161], v[238:241], v[80:83]
	v_mfma_f32_16x16x32_bf16 v[134:137], v[154:157], v[200:203], v[134:137]
	v_mfma_f32_16x16x32_bf16 v[130:133], v[170:173], v[200:203], v[130:133]
	v_mfma_f32_16x16x32_bf16 v[118:121], v[154:157], v[208:211], v[118:121]
	v_mfma_f32_16x16x32_bf16 v[114:117], v[170:173], v[208:211], v[114:117]
	v_mfma_f32_16x16x32_bf16 v[100:103], v[154:157], v[234:237], v[100:103]
	v_mfma_f32_16x16x32_bf16 v[96:99], v[170:173], v[234:237], v[96:99]
	v_mfma_f32_16x16x32_bf16 v[84:87], v[154:157], v[242:245], v[84:87]
	v_mfma_f32_16x16x32_bf16 v[80:83], v[170:173], v[242:245], v[80:83]
	v_mfma_f32_16x16x32_bf16 v[126:129], v[174:177], v[190:193], v[126:129]
	v_mfma_f32_16x16x32_bf16 v[122:125], v[182:185], v[190:193], v[122:125]
	v_mfma_f32_16x16x32_bf16 v[108:111], v[174:177], v[204:207], v[108:111]
	v_mfma_f32_16x16x32_bf16 v[104:107], v[182:185], v[204:207], v[104:107]
	v_mfma_f32_16x16x32_bf16 v[92:95], v[174:177], v[212:215], v[92:95]
	v_mfma_f32_16x16x32_bf16 v[88:91], v[182:185], v[212:215], v[88:91]
	v_mfma_f32_16x16x32_bf16 v[76:79], v[174:177], v[238:241], v[76:79]
	v_mfma_f32_16x16x32_bf16 v[72:75], v[182:185], v[238:241], v[72:75]
	v_mfma_f32_16x16x32_bf16 v[126:129], v[178:181], v[200:203], v[126:129]
	v_mfma_f32_16x16x32_bf16 v[122:125], v[186:189], v[200:203], v[122:125]
	v_mfma_f32_16x16x32_bf16 v[108:111], v[178:181], v[208:211], v[108:111]
	v_mfma_f32_16x16x32_bf16 v[104:107], v[186:189], v[208:211], v[104:107]
	v_mfma_f32_16x16x32_bf16 v[92:95], v[178:181], v[234:237], v[92:95]
	v_mfma_f32_16x16x32_bf16 v[88:91], v[186:189], v[234:237], v[88:91]
	v_mfma_f32_16x16x32_bf16 v[76:79], v[178:181], v[242:245], v[76:79]
	v_mfma_f32_16x16x32_bf16 v[72:75], v[186:189], v[242:245], v[72:75]
	s_setprio 0
	s_barrier
	s_add_i32 s8, s13, s81
	v_lshl_add_u64 v[162:163], s[94:95], 0, v[112:113]
	s_mov_b32 m0, s8
	ds_read_b128 v[190:193], v169 offset:16384
	ds_read_b128 v[200:203], v169 offset:17408
	ds_read_b128 v[204:207], v169 offset:18432
	ds_read_b128 v[208:211], v169 offset:19456
	ds_read_b128 v[212:215], v169 offset:20480
	ds_read_b128 v[234:237], v169 offset:21504
	ds_read_b128 v[238:241], v169 offset:22528
	ds_read_b128 v[242:245], v169 offset:23552
	global_load_lds_dwordx4 v112, s[94:95]
	s_add_i32 m0, s8, 0x2000
	s_add_u32 s8, s94, 0x40000
	v_lshl_add_u64 v[228:229], s[94:95], 0, v[142:143]
	s_addc_u32 s9, s95, 0
	s_add_i32 s13, s15, s81
	global_load_lds_dwordx4 v142, s[94:95]
	s_nop 0
	s_mov_b32 m0, s13
	v_lshl_add_u64 v[248:249], vcc, 0, v[140:141]
	global_load_lds_dwordx4 v112, s[8:9]
	s_nop 0
	s_add_i32 m0, s13, 0x2000
	s_nop 0
	global_load_lds_dwordx4 v142, s[8:9]
	v_lshl_add_u64 v[246:247], vcc, 0, v[138:139]
	s_mov_b32 m0, s11
	s_nop 0
	global_load_lds_dwordx4 v138, vcc
	s_mov_b32 m0, s19
	s_nop 0
	global_load_lds_dwordx4 v140, vcc
	s_waitcnt vmcnt(8)
	s_waitcnt lgkmcnt(0)
	s_barrier
; #define PG8_STAGE(bufoff, gbase, voff) do { _Pragma("unroll") for (int _i = 0; _i < 2; ++_i) \
;         __builtin_amdgcn_global_load_lds((const unsigned*)((const char*)(gbase) + (voff)[_i]), (LAS unsigned*)(lds + (bufoff) + ldsw + _i * 8192), 16, 0, 0); } while (0)
; #define PG8_LDA(dst, b, h) do { _Pragma("unroll") for (int m = 0; m < 4; ++m) _Pragma("unroll") for (int k = 0; k < 2; ++k) dst[m][k] = *(const LAS bf16x8*)(lds + PG8_SA(b, h) + aoff + m * 2048 + k * 1024); } while (0)
; #define PG8_LDB(dst, b, h) do { _Pragma("unroll") for (int n = 0; n < 2; ++n) _Pragma("unroll") for (int k = 0; k < 2; ++k) dst[n][k] = *(const LAS bf16x8*)(lds + PG8_SB(b, h) + boff + n * 2048 + k * 1024); } while (0)
; #define PG8_MMA(ai, bj, At, Bt) do { __builtin_amdgcn_s_setprio(1); _Pragma("unroll") for (int m = 0; m < 4; ++m) _Pragma("unroll") for (int n = 0; n < 2; ++n) _Pragma("unroll") for (int k = 0; k < 2; ++k) \
;         acc[ai][bj][m][n] = __builtin_amdgcn_mfma_f32_16x16x32_bf16(Bt[n][k], At[m][k], acc[ai][bj][m][n], 0, 0, 0); __builtin_amdgcn_s_setprio(0); } while (0)
; #define PG8_WAIT_V(n) asm volatile("s_waitcnt vmcnt(" #n ")" ::: "memory")
; #define PG8_WAIT_L(n) asm volatile("s_waitcnt lgkmcnt(" #n ")" ::: "memory")
; #define PG8_BAR __builtin_amdgcn_s_barrier()
; #define PG8_SCHED __builtin_amdgcn_sched_barrier(0)
; template <class Epi>
; __device__ __forceinline__ void gemm_phase(LAS unsigned char* lds, const Gemm g, const StaticOrder& S, const Epi& E, const int tid) {
;     ...
;             PG8_LDA(At, 0, 1); PG8_STAGE(PG8_SB(0, 0), b2, voffB); PG8_STAGE(PG8_SB(0, 1), b2 + hstepB, voffB); PG8_STAGE(PG8_SA(0, 0), a2, voffA);
;             PG8_WAIT_V(8); PG8_WAIT_L(0); PG8_BAR; PG8_MMA(1, 0, At, B0); PG8_MMA(1, 1, At, B1); PG8_BAR; PG8_SCHED;
;             PG8_LDB(B0, 1, 0); PG8_LDB(B1, 1, 1); PG8_SCHED; PG8_LDA(At, 1, 0); PG8_STAGE(PG8_SA(0, 1), a2 + hstepA, voffA);
;             PG8_WAIT_V(8); PG8_WAIT_L(0); PG8_BAR; PG8_MMA(0, 0, At, B0); PG8_MMA(0, 1, At, B1); PG8_BAR; PG8_SCHED;
;             PG8_LDA(At, 1, 1); PG8_STAGE(PG8_SB(1, 0), b3, voffB); PG8_STAGE(PG8_SB(1, 1), b3 + hstepB, voffB); PG8_STAGE(PG8_SA(1, 0), a3, voffA);
	s_setprio 1
	s_waitcnt lgkmcnt(0)
	v_mfma_f32_16x16x32_bf16 v[68:71], v[150:153], v[190:193], v[68:71]
	v_mfma_f32_16x16x32_bf16 v[64:67], v[158:161], v[190:193], v[64:67]
	v_mfma_f32_16x16x32_bf16 v[52:55], v[150:153], v[204:207], v[52:55]
	v_mfma_f32_16x16x32_bf16 v[48:51], v[158:161], v[204:207], v[48:51]
	v_mfma_f32_16x16x32_bf16 v[36:39], v[150:153], v[212:215], v[36:39]
	v_mfma_f32_16x16x32_bf16 v[32:35], v[158:161], v[212:215], v[32:35]
	v_mfma_f32_16x16x32_bf16 v[20:23], v[150:153], v[238:241], v[20:23]
	v_mfma_f32_16x16x32_bf16 v[16:19], v[158:161], v[238:241], v[16:19]
	v_mfma_f32_16x16x32_bf16 v[68:71], v[154:157], v[200:203], v[68:71]
	v_mfma_f32_16x16x32_bf16 v[64:67], v[170:173], v[200:203], v[64:67]
	v_mfma_f32_16x16x32_bf16 v[52:55], v[154:157], v[208:211], v[52:55]
	v_mfma_f32_16x16x32_bf16 v[48:51], v[170:173], v[208:211], v[48:51]
	v_mfma_f32_16x16x32_bf16 v[36:39], v[154:157], v[234:237], v[36:39]
	v_mfma_f32_16x16x32_bf16 v[32:35], v[170:173], v[234:237], v[32:35]
	v_mfma_f32_16x16x32_bf16 v[20:23], v[154:157], v[242:245], v[20:23]
	v_mfma_f32_16x16x32_bf16 v[16:19], v[170:173], v[242:245], v[16:19]
	v_mfma_f32_16x16x32_bf16 v[60:63], v[174:177], v[190:193], v[60:63]
	v_mfma_f32_16x16x32_bf16 v[56:59], v[182:185], v[190:193], v[56:59]
	v_mfma_f32_16x16x32_bf16 v[44:47], v[174:177], v[204:207], v[44:47]
	v_mfma_f32_16x16x32_bf16 v[40:43], v[182:185], v[204:207], v[40:43]
	v_mfma_f32_16x16x32_bf16 v[28:31], v[174:177], v[212:215], v[28:31]
	v_mfma_f32_16x16x32_bf16 v[24:27], v[182:185], v[212:215], v[24:27]
	v_mfma_f32_16x16x32_bf16 v[12:15], v[174:177], v[238:241], v[12:15]
	v_mfma_f32_16x16x32_bf16 v[8:11], v[182:185], v[238:241], v[8:11]
	v_mfma_f32_16x16x32_bf16 v[60:63], v[178:181], v[200:203], v[60:63]
	v_mfma_f32_16x16x32_bf16 v[56:59], v[186:189], v[200:203], v[56:59]
	v_mfma_f32_16x16x32_bf16 v[44:47], v[178:181], v[208:211], v[44:47]
	v_mfma_f32_16x16x32_bf16 v[40:43], v[186:189], v[208:211], v[40:43]
	v_mfma_f32_16x16x32_bf16 v[28:31], v[178:181], v[234:237], v[28:31]
	v_mfma_f32_16x16x32_bf16 v[24:27], v[186:189], v[234:237], v[24:27]
	v_mfma_f32_16x16x32_bf16 v[12:15], v[178:181], v[242:245], v[12:15]
	v_mfma_f32_16x16x32_bf16 v[8:11], v[186:189], v[242:245], v[8:11]
	s_setprio 0
	s_barrier
	s_add_i32 s13, 0, 0x18000
	s_add_i32 s31, 0, 0x1c000
	v_add_u32_e32 v170, s13, v167
	v_add_u32_e32 v186, s31, v167
	ds_read_b128 v[150:153], v170
	ds_read_b128 v[154:157], v170 offset:1024
	ds_read_b128 v[158:161], v170 offset:2048
	ds_read_b128 v[170:173], v170 offset:3072
	ds_read_b128 v[174:177], v186
	ds_read_b128 v[178:181], v186 offset:1024
	ds_read_b128 v[182:185], v186 offset:2048
	ds_read_b128 v[186:189], v186 offset:3072
	s_add_u32 s8, vcc_lo, 0x40000
	s_addc_u32 s9, vcc_hi, 0
	s_mov_b32 m0, s98
	s_nop 0
	ds_read_b128 v[190:193], v169 offset:32768
	ds_read_b128 v[200:203], v169 offset:33792
	ds_read_b128 v[204:207], v169 offset:34816
	ds_read_b128 v[208:211], v169 offset:35840
	ds_read_b128 v[212:215], v169 offset:36864
	ds_read_b128 v[234:237], v169 offset:37888
	ds_read_b128 v[238:241], v169 offset:38912
	ds_read_b128 v[242:245], v169 offset:39936
	global_load_lds_dwordx4 v138, s[8:9]
	v_lshl_add_u64 v[250:251], s[8:9], 0, v[140:141]
	s_mov_b32 m0, s99
	s_nop 0
	global_load_lds_dwordx4 v140, s[8:9]
	s_waitcnt vmcnt(8)
	s_waitcnt lgkmcnt(0)
	s_barrier
	s_setprio 1
	s_waitcnt lgkmcnt(0)
	v_mfma_f32_16x16x32_bf16 v[134:137], v[150:153], v[190:193], v[134:137]
	v_mfma_f32_16x16x32_bf16 v[130:133], v[158:161], v[190:193], v[130:133]
	v_mfma_f32_16x16x32_bf16 v[118:121], v[150:153], v[204:207], v[118:121]
	v_mfma_f32_16x16x32_bf16 v[114:117], v[158:161], v[204:207], v[114:117]
	v_mfma_f32_16x16x32_bf16 v[100:103], v[150:153], v[212:215], v[100:103]
	v_mfma_f32_16x16x32_bf16 v[96:99], v[158:161], v[212:215], v[96:99]
	v_mfma_f32_16x16x32_bf16 v[84:87], v[150:153], v[238:241], v[84:87]
	v_mfma_f32_16x16x32_bf16 v[80:83], v[158:161], v[238:241], v[80:83]
	v_mfma_f32_16x16x32_bf16 v[134:137], v[154:157], v[200:203], v[134:137]
	v_mfma_f32_16x16x32_bf16 v[130:133], v[170:173], v[200:203], v[130:133]
	v_mfma_f32_16x16x32_bf16 v[118:121], v[154:157], v[208:211], v[118:121]
	v_mfma_f32_16x16x32_bf16 v[114:117], v[170:173], v[208:211], v[114:117]
	v_mfma_f32_16x16x32_bf16 v[100:103], v[154:157], v[234:237], v[100:103]
	v_mfma_f32_16x16x32_bf16 v[96:99], v[170:173], v[234:237], v[96:99]
	v_mfma_f32_16x16x32_bf16 v[84:87], v[154:157], v[242:245], v[84:87]
	v_mfma_f32_16x16x32_bf16 v[80:83], v[170:173], v[242:245], v[80:83]
	v_mfma_f32_16x16x32_bf16 v[126:129], v[174:177], v[190:193], v[126:129]
	v_mfma_f32_16x16x32_bf16 v[122:125], v[182:185], v[190:193], v[122:125]
	v_mfma_f32_16x16x32_bf16 v[108:111], v[174:177], v[204:207], v[108:111]
	v_mfma_f32_16x16x32_bf16 v[104:107], v[182:185], v[204:207], v[104:107]
	v_mfma_f32_16x16x32_bf16 v[92:95], v[174:177], v[212:215], v[92:95]
	v_mfma_f32_16x16x32_bf16 v[88:91], v[182:185], v[212:215], v[88:91]
	v_mfma_f32_16x16x32_bf16 v[76:79], v[174:177], v[238:241], v[76:79]
	v_mfma_f32_16x16x32_bf16 v[72:75], v[182:185], v[238:241], v[72:75]
	v_mfma_f32_16x16x32_bf16 v[126:129], v[178:181], v[200:203], v[126:129]
	v_mfma_f32_16x16x32_bf16 v[122:125], v[186:189], v[200:203], v[122:125]
	v_mfma_f32_16x16x32_bf16 v[108:111], v[178:181], v[208:211], v[108:111]
	v_mfma_f32_16x16x32_bf16 v[104:107], v[186:189], v[208:211], v[104:107]
	v_mfma_f32_16x16x32_bf16 v[92:95], v[178:181], v[234:237], v[92:95]
	v_mfma_f32_16x16x32_bf16 v[88:91], v[186:189], v[234:237], v[88:91]
	v_mfma_f32_16x16x32_bf16 v[76:79], v[178:181], v[242:245], v[76:79]
	v_mfma_f32_16x16x32_bf16 v[72:75], v[186:189], v[242:245], v[72:75]
	s_setprio 0
	s_barrier
; #define PG8_STAGE(bufoff, gbase, voff) do { _Pragma("unroll") for (int _i = 0; _i < 2; ++_i) \
;         __builtin_amdgcn_global_load_lds((const unsigned*)((const char*)(gbase) + (voff)[_i]), (LAS unsigned*)(lds + (bufoff) + ldsw + _i * 8192), 16, 0, 0); } while (0)
; #define PG8_LDA(dst, b, h) do { _Pragma("unroll") for (int m = 0; m < 4; ++m) _Pragma("unroll") for (int k = 0; k < 2; ++k) dst[m][k] = *(const LAS bf16x8*)(lds + PG8_SA(b, h) + aoff + m * 2048 + k * 1024); } while (0)
; #define PG8_MMA(ai, bj, At, Bt) do { __builtin_amdgcn_s_setprio(1); _Pragma("unroll") for (int m = 0; m < 4; ++m) _Pragma("unroll") for (int n = 0; n < 2; ++n) _Pragma("unroll") for (int k = 0; k < 2; ++k) \
;         acc[ai][bj][m][n] = __builtin_amdgcn_mfma_f32_16x16x32_bf16(Bt[n][k], At[m][k], acc[ai][bj][m][n], 0, 0, 0); __builtin_amdgcn_s_setprio(0); } while (0)
; #define PG8_WAIT_V(n) asm volatile("s_waitcnt vmcnt(" #n ")" ::: "memory")
; #define PG8_WAIT_L(n) asm volatile("s_waitcnt lgkmcnt(" #n ")" ::: "memory")
; #define PG8_BAR __builtin_amdgcn_s_barrier()
; #define PG8_SCHED __builtin_amdgcn_sched_barrier(0)
; template <class Epi>
; __device__ __forceinline__ void gemm_phase(LAS unsigned char* lds, const Gemm g, const StaticOrder& S, const Epi& E, const int tid) {
;     ...
;             PG8_LDA(At, 1, 1); PG8_STAGE(PG8_SB(1, 0), b3, voffB); PG8_STAGE(PG8_SB(1, 1), b3 + hstepB, voffB); PG8_STAGE(PG8_SA(1, 0), a3, voffA);
;             PG8_WAIT_V(8); PG8_WAIT_L(0); PG8_BAR; PG8_MMA(1, 0, At, B0); PG8_MMA(1, 1, At, B1); PG8_BAR; PG8_SCHED;
;         }
	s_add_i32 s8, s13, s81
	v_lshl_add_u64 v[162:163], v[162:163], 0, s[24:25]
	s_mov_b32 m0, s8
	ds_read_b128 v[190:193], v169 offset:49152
	ds_read_b128 v[200:203], v169 offset:50176
	ds_read_b128 v[204:207], v169 offset:51200
	ds_read_b128 v[208:211], v169 offset:52224
	ds_read_b128 v[212:215], v169 offset:53248
	ds_read_b128 v[234:237], v169 offset:54272
	ds_read_b128 v[238:241], v169 offset:55296
	ds_read_b128 v[242:245], v169 offset:56320
	global_load_lds_dwordx4 v[162:163], off
	s_add_i32 m0, s8, 0x2000
	s_add_u32 s8, s94, 0x40080
	v_lshl_add_u64 v[162:163], v[228:229], 0, s[24:25]
	s_addc_u32 s9, s95, 0
	s_add_i32 s13, s31, s81
	global_load_lds_dwordx4 v[162:163], off
	s_nop 0
	s_mov_b32 m0, s13
	s_nop 0
	global_load_lds_dwordx4 v112, s[8:9]
	s_nop 0
	s_add_i32 m0, s13, 0x2000
	s_nop 0
	global_load_lds_dwordx4 v142, s[8:9]
	v_lshl_add_u64 v[162:163], v[246:247], 0, s[24:25]
	s_mov_b32 m0, s38
	s_nop 0
	global_load_lds_dwordx4 v[162:163], off
	v_lshl_add_u64 v[162:163], v[248:249], 0, s[24:25]
	s_mov_b32 m0, s39
	s_nop 0
	global_load_lds_dwordx4 v[162:163], off
	s_waitcnt vmcnt(8)
	s_waitcnt lgkmcnt(0)
	s_barrier
	s_setprio 1
	s_waitcnt lgkmcnt(0)
	v_mfma_f32_16x16x32_bf16 v[68:71], v[150:153], v[190:193], v[68:71]
	v_mfma_f32_16x16x32_bf16 v[64:67], v[158:161], v[190:193], v[64:67]
	v_mfma_f32_16x16x32_bf16 v[52:55], v[150:153], v[204:207], v[52:55]
	v_mfma_f32_16x16x32_bf16 v[48:51], v[158:161], v[204:207], v[48:51]
	v_mfma_f32_16x16x32_bf16 v[36:39], v[150:153], v[212:215], v[36:39]
	v_mfma_f32_16x16x32_bf16 v[32:35], v[158:161], v[212:215], v[32:35]
	v_mfma_f32_16x16x32_bf16 v[20:23], v[150:153], v[238:241], v[20:23]
	v_mfma_f32_16x16x32_bf16 v[16:19], v[158:161], v[238:241], v[16:19]
	v_mfma_f32_16x16x32_bf16 v[68:71], v[154:157], v[200:203], v[68:71]
	v_mfma_f32_16x16x32_bf16 v[64:67], v[170:173], v[200:203], v[64:67]
	v_mfma_f32_16x16x32_bf16 v[52:55], v[154:157], v[208:211], v[52:55]
	v_mfma_f32_16x16x32_bf16 v[48:51], v[170:173], v[208:211], v[48:51]
	v_mfma_f32_16x16x32_bf16 v[36:39], v[154:157], v[234:237], v[36:39]
	v_mfma_f32_16x16x32_bf16 v[32:35], v[170:173], v[234:237], v[32:35]
	v_mfma_f32_16x16x32_bf16 v[20:23], v[154:157], v[242:245], v[20:23]
	v_mfma_f32_16x16x32_bf16 v[16:19], v[170:173], v[242:245], v[16:19]
	v_mfma_f32_16x16x32_bf16 v[60:63], v[174:177], v[190:193], v[60:63]
	v_mfma_f32_16x16x32_bf16 v[56:59], v[182:185], v[190:193], v[56:59]
	v_mfma_f32_16x16x32_bf16 v[44:47], v[174:177], v[204:207], v[44:47]
	v_mfma_f32_16x16x32_bf16 v[40:43], v[182:185], v[204:207], v[40:43]
	v_mfma_f32_16x16x32_bf16 v[28:31], v[174:177], v[212:215], v[28:31]
	v_mfma_f32_16x16x32_bf16 v[24:27], v[182:185], v[212:215], v[24:27]
	v_mfma_f32_16x16x32_bf16 v[12:15], v[174:177], v[238:241], v[12:15]
	v_mfma_f32_16x16x32_bf16 v[8:11], v[182:185], v[238:241], v[8:11]
	v_mfma_f32_16x16x32_bf16 v[60:63], v[178:181], v[200:203], v[60:63]
	v_mfma_f32_16x16x32_bf16 v[56:59], v[186:189], v[200:203], v[56:59]
	v_mfma_f32_16x16x32_bf16 v[44:47], v[178:181], v[208:211], v[44:47]
	v_mfma_f32_16x16x32_bf16 v[40:43], v[186:189], v[208:211], v[40:43]
	v_mfma_f32_16x16x32_bf16 v[28:31], v[178:181], v[234:237], v[28:31]
	v_mfma_f32_16x16x32_bf16 v[24:27], v[186:189], v[234:237], v[24:27]
	v_mfma_f32_16x16x32_bf16 v[12:15], v[178:181], v[242:245], v[12:15]
	v_mfma_f32_16x16x32_bf16 v[8:11], v[186:189], v[242:245], v[8:11]
	s_setprio 0
	s_barrier
	s_add_i32 s85, s85, 2
	s_add_u32 s40, s40, 0x100
	s_addc_u32 s41, s41, 0
	s_add_u32 s46, s46, 0x100
	s_addc_u32 s57, s57, 0
	s_cmp_gt_u32 s85, 13
	s_cbranch_scc0 .LBB0_268
	s_and_b64 vcc, exec, s[82:83]
	s_cbranch_vccz .LBB0_271
	s_barrier

; #define PG8_STAGE(bufoff, gbase, voff) do { _Pragma("unroll") for (int _i = 0; _i < 2; ++_i) \
;         __builtin_amdgcn_global_load_lds((const unsigned*)((const char*)(gbase) + (voff)[_i]), (LAS unsigned*)(lds + (bufoff) + ldsw + _i * 8192), 16, 0, 0); } while (0)
; #define PG8_LDA(dst, b, h) do { _Pragma("unroll") for (int m = 0; m < 4; ++m) _Pragma("unroll") for (int k = 0; k < 2; ++k) dst[m][k] = *(const LAS bf16x8*)(lds + PG8_SA(b, h) + aoff + m * 2048 + k * 1024); } while (0)
; #define PG8_LDB(dst, b, h) do { _Pragma("unroll") for (int n = 0; n < 2; ++n) _Pragma("unroll") for (int k = 0; k < 2; ++k) dst[n][k] = *(const LAS bf16x8*)(lds + PG8_SB(b, h) + boff + n * 2048 + k * 1024); } while (0)
; #define PG8_MMA(ai, bj, At, Bt) do { __builtin_amdgcn_s_setprio(1); _Pragma("unroll") for (int m = 0; m < 4; ++m) _Pragma("unroll") for (int n = 0; n < 2; ++n) _Pragma("unroll") for (int k = 0; k < 2; ++k) \
;         acc[ai][bj][m][n] = __builtin_amdgcn_mfma_f32_16x16x32_bf16(Bt[n][k], At[m][k], acc[ai][bj][m][n], 0, 0, 0); __builtin_amdgcn_s_setprio(0); } while (0)
; #define PG8_WAIT_V(n) asm volatile("s_waitcnt vmcnt(" #n ")" ::: "memory")
; #define PG8_WAIT_L(n) asm volatile("s_waitcnt lgkmcnt(" #n ")" ::: "memory")
; #define PG8_BAR __builtin_amdgcn_s_barrier()
; #define PG8_SCHED __builtin_amdgcn_sched_barrier(0)
; template <class Epi>
; __device__ __forceinline__ void gemm_phase(LAS unsigned char* lds, const Gemm g, const StaticOrder& S, const Epi& E, const int tid) {
;     ...
;         for (int t = 0; t < nt; t += 2) {
;             const bool last = (t == nt - 2);
;             const char* a1 = cA + (size_t)(t + 1) * kstep + ((t + 1) >= 8 ? xtra : 0);
;             const char* a2 = last ? nA : cA + (size_t)(t + 2) * kstep + ((t + 2) >= 8 ? xtra : 0); const char* b2 = last ? nB : cB + (size_t)(t + 2) * kstep;
;             const char* a3 = a2 + kstep; const char* b3 = b2 + kstep;
;             PG8_LDB(B0, 0, 0); PG8_LDB(B1, 0, 1); PG8_SCHED; PG8_LDA(At, 0, 0); PG8_STAGE(PG8_SA(1, 1), a1 + hstepA, voffA);
;             PG8_WAIT_V(8); PG8_WAIT_L(0); PG8_BAR; PG8_MMA(0, 0, At, B0); PG8_MMA(0, 1, At, B1); PG8_BAR; PG8_SCHED;
;             PG8_LDA(At, 0, 1); PG8_STAGE(PG8_SB(0, 0), b2, voffB); PG8_STAGE(PG8_SB(0, 1), b2 + hstepB, voffB); PG8_STAGE(PG8_SA(0, 0), a2, voffA);
.LBB0_356:
	s_add_u32 s8, s42, 0xfffc0080
	s_addc_u32 s9, s43, -1
	s_add_i32 s13, 0, 0x10000
	v_add_u32_e32 v168, s13, v161
	v_add_u32_e32 v184, s15, v161
	ds_read_b128 v[150:153], v168
	ds_read_b128 v[154:157], v168 offset:1024
	ds_read_b128 v[164:167], v168 offset:2048
	ds_read_b128 v[168:171], v168 offset:3072
	ds_read_b128 v[172:175], v184
	ds_read_b128 v[176:179], v184 offset:1024
	ds_read_b128 v[180:183], v184 offset:2048
	ds_read_b128 v[184:187], v184 offset:3072
	s_cmp_eq_u32 s97, 12
	s_cselect_b32 s95, s98, s9
	s_cselect_b32 s94, s99, s8
	s_cselect_b32 s93, s83, s96
	s_cselect_b32 s92, vcc_lo, vcc_hi
	s_nop 0
	s_add_i32 m0, s19, 0xc000
	ds_read_b128 v[188:191], v163
	ds_read_b128 v[200:203], v163 offset:1024
	ds_read_b128 v[204:207], v163 offset:2048
	ds_read_b128 v[208:211], v163 offset:3072
	ds_read_b128 v[212:215], v163 offset:4096
	ds_read_b128 v[234:237], v163 offset:5120
	ds_read_b128 v[238:241], v163 offset:6144
	ds_read_b128 v[242:245], v163 offset:7168
	global_load_lds_dwordx4 v146, s[42:43]
	s_nop 0
	s_add_i32 m0, s19, 0xe000
	s_nop 0
	global_load_lds_dwordx4 v148, s[42:43]
	s_waitcnt vmcnt(8)
	s_waitcnt lgkmcnt(0)
	s_barrier
	s_setprio 1
	s_waitcnt lgkmcnt(0)
	v_mfma_f32_16x16x32_bf16 v[134:137], v[150:153], v[188:191], v[134:137]
	v_mfma_f32_16x16x32_bf16 v[130:133], v[164:167], v[188:191], v[130:133]
	v_mfma_f32_16x16x32_bf16 v[122:125], v[150:153], v[204:207], v[122:125]
	v_mfma_f32_16x16x32_bf16 v[114:117], v[164:167], v[204:207], v[114:117]
	v_mfma_f32_16x16x32_bf16 v[104:107], v[150:153], v[212:215], v[104:107]
	v_mfma_f32_16x16x32_bf16 v[96:99], v[164:167], v[212:215], v[96:99]
	v_mfma_f32_16x16x32_bf16 v[88:91], v[150:153], v[238:241], v[88:91]
	v_mfma_f32_16x16x32_bf16 v[80:83], v[164:167], v[238:241], v[80:83]
	v_mfma_f32_16x16x32_bf16 v[134:137], v[154:157], v[200:203], v[134:137]
	v_mfma_f32_16x16x32_bf16 v[130:133], v[168:171], v[200:203], v[130:133]
	v_mfma_f32_16x16x32_bf16 v[122:125], v[154:157], v[208:211], v[122:125]
	v_mfma_f32_16x16x32_bf16 v[114:117], v[168:171], v[208:211], v[114:117]
	v_mfma_f32_16x16x32_bf16 v[104:107], v[154:157], v[234:237], v[104:107]
	v_mfma_f32_16x16x32_bf16 v[96:99], v[168:171], v[234:237], v[96:99]
	v_mfma_f32_16x16x32_bf16 v[88:91], v[154:157], v[242:245], v[88:91]
	v_mfma_f32_16x16x32_bf16 v[80:83], v[168:171], v[242:245], v[80:83]
	v_mfma_f32_16x16x32_bf16 v[126:129], v[172:175], v[188:191], v[126:129]
	v_mfma_f32_16x16x32_bf16 v[118:121], v[180:183], v[188:191], v[118:121]
	v_mfma_f32_16x16x32_bf16 v[108:111], v[172:175], v[204:207], v[108:111]
	v_mfma_f32_16x16x32_bf16 v[100:103], v[180:183], v[204:207], v[100:103]
	v_mfma_f32_16x16x32_bf16 v[92:95], v[172:175], v[212:215], v[92:95]
	v_mfma_f32_16x16x32_bf16 v[84:87], v[180:183], v[212:215], v[84:87]
	v_mfma_f32_16x16x32_bf16 v[76:79], v[172:175], v[238:241], v[76:79]
	v_mfma_f32_16x16x32_bf16 v[72:75], v[180:183], v[238:241], v[72:75]
	v_mfma_f32_16x16x32_bf16 v[126:129], v[176:179], v[200:203], v[126:129]
	v_mfma_f32_16x16x32_bf16 v[118:121], v[184:187], v[200:203], v[118:121]
	v_mfma_f32_16x16x32_bf16 v[108:111], v[176:179], v[208:211], v[108:111]
	v_mfma_f32_16x16x32_bf16 v[100:103], v[184:187], v[208:211], v[100:103]
	v_mfma_f32_16x16x32_bf16 v[92:95], v[176:179], v[234:237], v[92:95]
	v_mfma_f32_16x16x32_bf16 v[84:87], v[184:187], v[234:237], v[84:87]
	v_mfma_f32_16x16x32_bf16 v[76:79], v[176:179], v[242:245], v[76:79]
	v_mfma_f32_16x16x32_bf16 v[72:75], v[184:187], v[242:245], v[72:75]
	s_setprio 0
	s_barrier
	s_add_i32 s8, s13, s17
	v_lshl_add_u64 v[192:193], s[92:93], 0, v[112:113]
	s_mov_b32 m0, s8
	ds_read_b128 v[188:191], v163 offset:16384
	ds_read_b128 v[200:203], v163 offset:17408
	ds_read_b128 v[204:207], v163 offset:18432
	ds_read_b128 v[208:211], v163 offset:19456
	ds_read_b128 v[212:215], v163 offset:20480
	ds_read_b128 v[234:237], v163 offset:21504
	ds_read_b128 v[238:241], v163 offset:22528
	ds_read_b128 v[242:245], v163 offset:23552
	global_load_lds_dwordx4 v112, s[92:93]
	s_add_i32 m0, s8, 0x2000
	s_add_u32 s8, s92, 0x40000
	v_lshl_add_u64 v[246:247], s[92:93], 0, v[142:143]
	s_addc_u32 s9, s93, 0
	s_add_i32 s13, s15, s17
	global_load_lds_dwordx4 v142, s[92:93]
	s_nop 0
	s_mov_b32 m0, s13
	v_lshl_add_u64 v[250:251], s[94:95], 0, v[140:141]
	global_load_lds_dwordx4 v112, s[8:9]
	s_nop 0
	s_add_i32 m0, s13, 0x2000
	s_nop 0
	global_load_lds_dwordx4 v142, s[8:9]
	v_lshl_add_u64 v[248:249], s[94:95], 0, v[138:139]
	s_mov_b32 m0, s19
	s_nop 0
	global_load_lds_dwordx4 v138, s[94:95]
	s_mov_b32 m0, s23
	s_nop 0
	global_load_lds_dwordx4 v140, s[94:95]
	s_waitcnt vmcnt(8)
	s_waitcnt lgkmcnt(0)
	s_barrier
; #define PG8_STAGE(bufoff, gbase, voff) do { _Pragma("unroll") for (int _i = 0; _i < 2; ++_i) \
;         __builtin_amdgcn_global_load_lds((const unsigned*)((const char*)(gbase) + (voff)[_i]), (LAS unsigned*)(lds + (bufoff) + ldsw + _i * 8192), 16, 0, 0); } while (0)
; #define PG8_LDA(dst, b, h) do { _Pragma("unroll") for (int m = 0; m < 4; ++m) _Pragma("unroll") for (int k = 0; k < 2; ++k) dst[m][k] = *(const LAS bf16x8*)(lds + PG8_SA(b, h) + aoff + m * 2048 + k * 1024); } while (0)
; #define PG8_LDB(dst, b, h) do { _Pragma("unroll") for (int n = 0; n < 2; ++n) _Pragma("unroll") for (int k = 0; k < 2; ++k) dst[n][k] = *(const LAS bf16x8*)(lds + PG8_SB(b, h) + boff + n * 2048 + k * 1024); } while (0)
; #define PG8_MMA(ai, bj, At, Bt) do { __builtin_amdgcn_s_setprio(1); _Pragma("unroll") for (int m = 0; m < 4; ++m) _Pragma("unroll") for (int n = 0; n < 2; ++n) _Pragma("unroll") for (int k = 0; k < 2; ++k) \
;         acc[ai][bj][m][n] = __builtin_amdgcn_mfma_f32_16x16x32_bf16(Bt[n][k], At[m][k], acc[ai][bj][m][n], 0, 0, 0); __builtin_amdgcn_s_setprio(0); } while (0)
; #define PG8_WAIT_V(n) asm volatile("s_waitcnt vmcnt(" #n ")" ::: "memory")
; #define PG8_WAIT_L(n) asm volatile("s_waitcnt lgkmcnt(" #n ")" ::: "memory")
; #define PG8_BAR __builtin_amdgcn_s_barrier()
; #define PG8_SCHED __builtin_amdgcn_sched_barrier(0)
; template <class Epi>
; __device__ __forceinline__ void gemm_phase(LAS unsigned char* lds, const Gemm g, const StaticOrder& S, const Epi& E, const int tid) {
;     ...
;             PG8_LDA(At, 0, 1); PG8_STAGE(PG8_SB(0, 0), b2, voffB); PG8_STAGE(PG8_SB(0, 1), b2 + hstepB, voffB); PG8_STAGE(PG8_SA(0, 0), a2, voffA);
;             PG8_WAIT_V(8); PG8_WAIT_L(0); PG8_BAR; PG8_MMA(1, 0, At, B0); PG8_MMA(1, 1, At, B1); PG8_BAR; PG8_SCHED;
;             PG8_LDB(B0, 1, 0); PG8_LDB(B1, 1, 1); PG8_SCHED; PG8_LDA(At, 1, 0); PG8_STAGE(PG8_SA(0, 1), a2 + hstepA, voffA);
;             PG8_WAIT_V(8); PG8_WAIT_L(0); PG8_BAR; PG8_MMA(0, 0, At, B0); PG8_MMA(0, 1, At, B1); PG8_BAR; PG8_SCHED;
;             PG8_LDA(At, 1, 1); PG8_STAGE(PG8_SB(1, 0), b3, voffB); PG8_STAGE(PG8_SB(1, 1), b3 + hstepB, voffB); PG8_STAGE(PG8_SA(1, 0), a3, voffA);
	s_setprio 1
	s_waitcnt lgkmcnt(0)
	v_mfma_f32_16x16x32_bf16 v[68:71], v[150:153], v[188:191], v[68:71]
	v_mfma_f32_16x16x32_bf16 v[64:67], v[164:167], v[188:191], v[64:67]
	v_mfma_f32_16x16x32_bf16 v[56:59], v[150:153], v[204:207], v[56:59]
	v_mfma_f32_16x16x32_bf16 v[48:51], v[164:167], v[204:207], v[48:51]
	v_mfma_f32_16x16x32_bf16 v[40:43], v[150:153], v[212:215], v[40:43]
	v_mfma_f32_16x16x32_bf16 v[32:35], v[164:167], v[212:215], v[32:35]
	v_mfma_f32_16x16x32_bf16 v[24:27], v[150:153], v[238:241], v[24:27]
	v_mfma_f32_16x16x32_bf16 v[16:19], v[164:167], v[238:241], v[16:19]
	v_mfma_f32_16x16x32_bf16 v[68:71], v[154:157], v[200:203], v[68:71]
	v_mfma_f32_16x16x32_bf16 v[64:67], v[168:171], v[200:203], v[64:67]
	v_mfma_f32_16x16x32_bf16 v[56:59], v[154:157], v[208:211], v[56:59]
	v_mfma_f32_16x16x32_bf16 v[48:51], v[168:171], v[208:211], v[48:51]
	v_mfma_f32_16x16x32_bf16 v[40:43], v[154:157], v[234:237], v[40:43]
	v_mfma_f32_16x16x32_bf16 v[32:35], v[168:171], v[234:237], v[32:35]
	v_mfma_f32_16x16x32_bf16 v[24:27], v[154:157], v[242:245], v[24:27]
	v_mfma_f32_16x16x32_bf16 v[16:19], v[168:171], v[242:245], v[16:19]
	v_mfma_f32_16x16x32_bf16 v[60:63], v[172:175], v[188:191], v[60:63]
	v_mfma_f32_16x16x32_bf16 v[52:55], v[180:183], v[188:191], v[52:55]
	v_mfma_f32_16x16x32_bf16 v[44:47], v[172:175], v[204:207], v[44:47]
	v_mfma_f32_16x16x32_bf16 v[36:39], v[180:183], v[204:207], v[36:39]
	v_mfma_f32_16x16x32_bf16 v[28:31], v[172:175], v[212:215], v[28:31]
	v_mfma_f32_16x16x32_bf16 v[20:23], v[180:183], v[212:215], v[20:23]
	v_mfma_f32_16x16x32_bf16 v[12:15], v[172:175], v[238:241], v[12:15]
	v_mfma_f32_16x16x32_bf16 v[8:11], v[180:183], v[238:241], v[8:11]
	v_mfma_f32_16x16x32_bf16 v[60:63], v[176:179], v[200:203], v[60:63]
	v_mfma_f32_16x16x32_bf16 v[52:55], v[184:187], v[200:203], v[52:55]
	v_mfma_f32_16x16x32_bf16 v[44:47], v[176:179], v[208:211], v[44:47]
	v_mfma_f32_16x16x32_bf16 v[36:39], v[184:187], v[208:211], v[36:39]
	v_mfma_f32_16x16x32_bf16 v[28:31], v[176:179], v[234:237], v[28:31]
	v_mfma_f32_16x16x32_bf16 v[20:23], v[184:187], v[234:237], v[20:23]
	v_mfma_f32_16x16x32_bf16 v[12:15], v[176:179], v[242:245], v[12:15]
	v_mfma_f32_16x16x32_bf16 v[8:11], v[184:187], v[242:245], v[8:11]
	s_setprio 0
	s_barrier
	s_add_i32 s13, 0, 0x18000
	s_add_i32 s31, 0, 0x1c000
	v_add_u32_e32 v168, s13, v161
	v_add_u32_e32 v184, s31, v161
	ds_read_b128 v[150:153], v168
	ds_read_b128 v[154:157], v168 offset:1024
	ds_read_b128 v[164:167], v168 offset:2048
	ds_read_b128 v[168:171], v168 offset:3072
	ds_read_b128 v[172:175], v184
	ds_read_b128 v[176:179], v184 offset:1024
	ds_read_b128 v[180:183], v184 offset:2048
	ds_read_b128 v[184:187], v184 offset:3072
	s_add_u32 s8, s94, 0x40000
	s_addc_u32 s9, s95, 0
	s_mov_b32 m0, s28
	s_nop 0
	ds_read_b128 v[188:191], v163 offset:32768
	ds_read_b128 v[200:203], v163 offset:33792
	ds_read_b128 v[204:207], v163 offset:34816
	ds_read_b128 v[208:211], v163 offset:35840
	ds_read_b128 v[212:215], v163 offset:36864
	ds_read_b128 v[234:237], v163 offset:37888
	ds_read_b128 v[238:241], v163 offset:38912
	ds_read_b128 v[242:245], v163 offset:39936
	global_load_lds_dwordx4 v138, s[8:9]
	v_lshl_add_u64 v[228:229], s[8:9], 0, v[140:141]
	s_mov_b32 m0, s30
	s_nop 0
	global_load_lds_dwordx4 v140, s[8:9]
	s_waitcnt vmcnt(8)
	s_waitcnt lgkmcnt(0)
	s_barrier
	s_setprio 1
	s_waitcnt lgkmcnt(0)
	v_mfma_f32_16x16x32_bf16 v[134:137], v[150:153], v[188:191], v[134:137]
	v_mfma_f32_16x16x32_bf16 v[130:133], v[164:167], v[188:191], v[130:133]
	v_mfma_f32_16x16x32_bf16 v[122:125], v[150:153], v[204:207], v[122:125]
	v_mfma_f32_16x16x32_bf16 v[114:117], v[164:167], v[204:207], v[114:117]
	v_mfma_f32_16x16x32_bf16 v[104:107], v[150:153], v[212:215], v[104:107]
	v_mfma_f32_16x16x32_bf16 v[96:99], v[164:167], v[212:215], v[96:99]
	v_mfma_f32_16x16x32_bf16 v[88:91], v[150:153], v[238:241], v[88:91]
	v_mfma_f32_16x16x32_bf16 v[80:83], v[164:167], v[238:241], v[80:83]
	v_mfma_f32_16x16x32_bf16 v[134:137], v[154:157], v[200:203], v[134:137]
	v_mfma_f32_16x16x32_bf16 v[130:133], v[168:171], v[200:203], v[130:133]
	v_mfma_f32_16x16x32_bf16 v[122:125], v[154:157], v[208:211], v[122:125]
	v_mfma_f32_16x16x32_bf16 v[114:117], v[168:171], v[208:211], v[114:117]
	v_mfma_f32_16x16x32_bf16 v[104:107], v[154:157], v[234:237], v[104:107]
	v_mfma_f32_16x16x32_bf16 v[96:99], v[168:171], v[234:237], v[96:99]
	v_mfma_f32_16x16x32_bf16 v[88:91], v[154:157], v[242:245], v[88:91]
	v_mfma_f32_16x16x32_bf16 v[80:83], v[168:171], v[242:245], v[80:83]
	v_mfma_f32_16x16x32_bf16 v[126:129], v[172:175], v[188:191], v[126:129]
	v_mfma_f32_16x16x32_bf16 v[118:121], v[180:183], v[188:191], v[118:121]
	v_mfma_f32_16x16x32_bf16 v[108:111], v[172:175], v[204:207], v[108:111]
	v_mfma_f32_16x16x32_bf16 v[100:103], v[180:183], v[204:207], v[100:103]
	v_mfma_f32_16x16x32_bf16 v[92:95], v[172:175], v[212:215], v[92:95]
	v_mfma_f32_16x16x32_bf16 v[84:87], v[180:183], v[212:215], v[84:87]
	v_mfma_f32_16x16x32_bf16 v[76:79], v[172:175], v[238:241], v[76:79]
	v_mfma_f32_16x16x32_bf16 v[72:75], v[180:183], v[238:241], v[72:75]
	v_mfma_f32_16x16x32_bf16 v[126:129], v[176:179], v[200:203], v[126:129]
	v_mfma_f32_16x16x32_bf16 v[118:121], v[184:187], v[200:203], v[118:121]
	v_mfma_f32_16x16x32_bf16 v[108:111], v[176:179], v[208:211], v[108:111]
	v_mfma_f32_16x16x32_bf16 v[100:103], v[184:187], v[208:211], v[100:103]
	v_mfma_f32_16x16x32_bf16 v[92:95], v[176:179], v[234:237], v[92:95]
	v_mfma_f32_16x16x32_bf16 v[84:87], v[184:187], v[234:237], v[84:87]
	v_mfma_f32_16x16x32_bf16 v[76:79], v[176:179], v[242:245], v[76:79]
	v_mfma_f32_16x16x32_bf16 v[72:75], v[184:187], v[242:245], v[72:75]
	s_setprio 0
	s_barrier
; #define PG8_STAGE(bufoff, gbase, voff) do { _Pragma("unroll") for (int _i = 0; _i < 2; ++_i) \
;         __builtin_amdgcn_global_load_lds((const unsigned*)((const char*)(gbase) + (voff)[_i]), (LAS unsigned*)(lds + (bufoff) + ldsw + _i * 8192), 16, 0, 0); } while (0)
; #define PG8_LDA(dst, b, h) do { _Pragma("unroll") for (int m = 0; m < 4; ++m) _Pragma("unroll") for (int k = 0; k < 2; ++k) dst[m][k] = *(const LAS bf16x8*)(lds + PG8_SA(b, h) + aoff + m * 2048 + k * 1024); } while (0)
; #define PG8_MMA(ai, bj, At, Bt) do { __builtin_amdgcn_s_setprio(1); _Pragma("unroll") for (int m = 0; m < 4; ++m) _Pragma("unroll") for (int n = 0; n < 2; ++n) _Pragma("unroll") for (int k = 0; k < 2; ++k) \
;         acc[ai][bj][m][n] = __builtin_amdgcn_mfma_f32_16x16x32_bf16(Bt[n][k], At[m][k], acc[ai][bj][m][n], 0, 0, 0); __builtin_amdgcn_s_setprio(0); } while (0)
; #define PG8_WAIT_V(n) asm volatile("s_waitcnt vmcnt(" #n ")" ::: "memory")
; #define PG8_WAIT_L(n) asm volatile("s_waitcnt lgkmcnt(" #n ")" ::: "memory")
; #define PG8_BAR __builtin_amdgcn_s_barrier()
; #define PG8_SCHED __builtin_amdgcn_sched_barrier(0)
; template <class Epi>
; __device__ __forceinline__ void gemm_phase(LAS unsigned char* lds, const Gemm g, const StaticOrder& S, const Epi& E, const int tid) {
;     ...
;             PG8_LDA(At, 1, 1); PG8_STAGE(PG8_SB(1, 0), b3, voffB); PG8_STAGE(PG8_SB(1, 1), b3 + hstepB, voffB); PG8_STAGE(PG8_SA(1, 0), a3, voffA);
;             PG8_WAIT_V(8); PG8_WAIT_L(0); PG8_BAR; PG8_MMA(1, 0, At, B0); PG8_MMA(1, 1, At, B1); PG8_BAR; PG8_SCHED;
;         }
	s_add_i32 s8, s13, s17
	v_lshl_add_u64 v[192:193], v[192:193], 0, s[24:25]
	s_mov_b32 m0, s8
	ds_read_b128 v[188:191], v163 offset:49152
	ds_read_b128 v[200:203], v163 offset:50176
	ds_read_b128 v[204:207], v163 offset:51200
	ds_read_b128 v[208:211], v163 offset:52224
	ds_read_b128 v[212:215], v163 offset:53248
	ds_read_b128 v[234:237], v163 offset:54272
	ds_read_b128 v[238:241], v163 offset:55296
	ds_read_b128 v[242:245], v163 offset:56320
	global_load_lds_dwordx4 v[192:193], off
	s_add_i32 m0, s8, 0x2000
	s_add_u32 s8, s92, 0x40080
	v_lshl_add_u64 v[192:193], v[246:247], 0, s[24:25]
	s_addc_u32 s9, s93, 0
	s_add_i32 s13, s31, s17
	global_load_lds_dwordx4 v[192:193], off
	s_nop 0
	s_mov_b32 m0, s13
	s_nop 0
	global_load_lds_dwordx4 v112, s[8:9]
	s_nop 0
	s_add_i32 m0, s13, 0x2000
	s_nop 0
	global_load_lds_dwordx4 v142, s[8:9]
	v_lshl_add_u64 v[192:193], v[248:249], 0, s[24:25]
	s_mov_b32 m0, s36
	s_nop 0
	global_load_lds_dwordx4 v[192:193], off
	v_lshl_add_u64 v[192:193], v[250:251], 0, s[24:25]
	s_mov_b32 m0, s37
	s_nop 0
	global_load_lds_dwordx4 v[192:193], off
	s_waitcnt vmcnt(8)
	s_waitcnt lgkmcnt(0)
	s_barrier
	s_setprio 1
	s_waitcnt lgkmcnt(0)
	v_mfma_f32_16x16x32_bf16 v[68:71], v[150:153], v[188:191], v[68:71]
	v_mfma_f32_16x16x32_bf16 v[64:67], v[164:167], v[188:191], v[64:67]
	v_mfma_f32_16x16x32_bf16 v[56:59], v[150:153], v[204:207], v[56:59]
	v_mfma_f32_16x16x32_bf16 v[48:51], v[164:167], v[204:207], v[48:51]
	v_mfma_f32_16x16x32_bf16 v[40:43], v[150:153], v[212:215], v[40:43]
	v_mfma_f32_16x16x32_bf16 v[32:35], v[164:167], v[212:215], v[32:35]
	v_mfma_f32_16x16x32_bf16 v[24:27], v[150:153], v[238:241], v[24:27]
	v_mfma_f32_16x16x32_bf16 v[16:19], v[164:167], v[238:241], v[16:19]
	v_mfma_f32_16x16x32_bf16 v[68:71], v[154:157], v[200:203], v[68:71]
	v_mfma_f32_16x16x32_bf16 v[64:67], v[168:171], v[200:203], v[64:67]
	v_mfma_f32_16x16x32_bf16 v[56:59], v[154:157], v[208:211], v[56:59]
	v_mfma_f32_16x16x32_bf16 v[48:51], v[168:171], v[208:211], v[48:51]
	v_mfma_f32_16x16x32_bf16 v[40:43], v[154:157], v[234:237], v[40:43]
	v_mfma_f32_16x16x32_bf16 v[32:35], v[168:171], v[234:237], v[32:35]
	v_mfma_f32_16x16x32_bf16 v[24:27], v[154:157], v[242:245], v[24:27]
	v_mfma_f32_16x16x32_bf16 v[16:19], v[168:171], v[242:245], v[16:19]
	v_mfma_f32_16x16x32_bf16 v[60:63], v[172:175], v[188:191], v[60:63]
	v_mfma_f32_16x16x32_bf16 v[52:55], v[180:183], v[188:191], v[52:55]
	v_mfma_f32_16x16x32_bf16 v[44:47], v[172:175], v[204:207], v[44:47]
	v_mfma_f32_16x16x32_bf16 v[36:39], v[180:183], v[204:207], v[36:39]
	v_mfma_f32_16x16x32_bf16 v[28:31], v[172:175], v[212:215], v[28:31]
	v_mfma_f32_16x16x32_bf16 v[20:23], v[180:183], v[212:215], v[20:23]
	v_mfma_f32_16x16x32_bf16 v[12:15], v[172:175], v[238:241], v[12:15]
	v_mfma_f32_16x16x32_bf16 v[8:11], v[180:183], v[238:241], v[8:11]
	v_mfma_f32_16x16x32_bf16 v[60:63], v[176:179], v[200:203], v[60:63]
	v_mfma_f32_16x16x32_bf16 v[52:55], v[184:187], v[200:203], v[52:55]
	v_mfma_f32_16x16x32_bf16 v[44:47], v[176:179], v[208:211], v[44:47]
	v_mfma_f32_16x16x32_bf16 v[36:39], v[184:187], v[208:211], v[36:39]
	v_mfma_f32_16x16x32_bf16 v[28:31], v[176:179], v[234:237], v[28:31]
	v_mfma_f32_16x16x32_bf16 v[20:23], v[184:187], v[234:237], v[20:23]
	v_mfma_f32_16x16x32_bf16 v[12:15], v[176:179], v[242:245], v[12:15]
	v_mfma_f32_16x16x32_bf16 v[8:11], v[184:187], v[242:245], v[8:11]
	s_setprio 0
	s_barrier
	s_add_i32 s97, s97, 2
	s_add_u32 s42, s42, 0x100
	s_addc_u32 s43, s43, 0
	s_add_u32 vcc_hi, vcc_hi, 0x100
	s_addc_u32 s96, s96, 0
	s_cmp_gt_u32 s97, 13
	s_cbranch_scc0 .LBB0_356
	s_and_b64 vcc, exec, s[80:81]
	s_cbranch_vccz .LBB0_359
	s_barrier
